# static priority: one s_setprio 1 for waves 4-7 (wr=1 half) per GEMM phase, hipcc per-MFMA-block priority flips deleted; on top of chain+prep3+novalu
# speedup vs baseline: 1.0040x; 1.0040x over previous
; #define PG8_STAGE(bufoff, gbase, voff) do { _Pragma("unroll") for (int _i = 0; _i < 2; ++_i) \
;         __builtin_amdgcn_global_load_lds((const unsigned*)((const char*)(gbase) + (voff)[_i]), (PG8_LAS unsigned*)(lds + (bufoff) + ldsw + _i * 8192), 16, 0, 0); } while (0)
; #define PG8_WAIT_V(n) asm volatile("s_waitcnt vmcnt(" #n ")" ::: "memory")
; #define PG8_BAR __builtin_amdgcn_s_barrier()
; template <class Epi, class Sched, bool ALIGN_EPI = false, bool SP2 = false>
; __device__ __forceinline__ void gemm_phase(PG8_LAS unsigned char* lds, const Gemm g, const Sched& S, const Epi& E) {
;     const int tid = threadIdx.x, wid = __builtin_amdgcn_readfirstlane(tid >> 6), lane = tid & 63, wr = wid >> 2, wc = wid & 3, fr = lane & 15, fq = lane >> 4;
;     const int K = g.K, nt = K / BK;
;     unsigned voffA[2], voffB[2];
; #pragma unroll
;     for (int i = 0; i < 2; ++i) { int R, C; stage_rc(tid * 16 + i * 8192, R, C); const int Rb = Epi::PERM ? ((R & ~31) + perm32(R & 31)) : R;
;         voffA[i] = (unsigned)(R * K + C) * 2u; voffB[i] = (unsigned)(Rb * K + C) * 2u; }
;     ...
;     const char* cA = (const char*)g.A + (size_t)cur.pm * tstep; const char* cB = (const char*)g.Bt + (size_t)cur.pn * tstep;
;     S.a_ready(cur);
;     if constexpr (SP2) {
;         PG8_STAGE(PG8_SB(0, 0), cB, voffB); PG8_STAGE(PG8_SB(0, 1), cB + hstep, voffB); PG8_STAGE(PG8_SA(0, 0), cA, voffA); PG8_STAGE(PG8_SA(0, 1), cA + hstep, voffA);
;         if (wr == 1) PG8_BAR;
;         PG8_WAIT_V(2); PG8_BAR;
;         PG8_STAGE(PG8_SB(1, 0), cB + kstep, voffB); PG8_STAGE(PG8_SA(1, 0), cA + kstep, voffA); PG8_STAGE(PG8_SB(1, 1), cB + hstep + kstep, voffB);
;         PG8_WAIT_V(6); PG8_BAR;
;     } else {
;         PG8_STAGE(PG8_SB(0, 0), cB, voffB); PG8_STAGE(PG8_SA(0, 0), cA, voffA); PG8_STAGE(PG8_SB(0, 1), cB + hstep, voffB); PG8_STAGE(PG8_SA(0, 1), cA + hstep, voffA);
;         if (wr == 1) PG8_BAR;
.LBB0_194:
	s_or_b64 exec, exec, s[0:1]
	s_cmpk_gt_i32 s33, 0xdbf
	v_readfirstlane_b32 s1, v131
	s_barrier
	s_cbranch_scc1 .LBB0_282
	v_lshrrev_b32_e32 v4, 1, v131
	v_and_b32_e32 v130, 24, v4
	v_and_b32_e32 v4, 4, v94
	v_bfe_u32 v5, v131, 2, 2
	v_bfe_u32 v12, v131, 2, 4
	v_or3_b32 v4, v4, v5, v130
	v_lshrrev_b32_e32 v5, 3, v131
	s_movk_i32 s0, 0x70
	v_and_or_b32 v6, v5, s0, v12
	s_movk_i32 s0, 0x60
	s_ashr_i32 s37, s33, 31
	v_and_or_b32 v5, v5, s0, v4
	s_lshr_b32 s0, s37, 29
	s_add_i32 s0, s33, s0
	s_lshr_b32 s10, s1, 6
	s_ashr_i32 s2, s0, 3
	s_and_b32 s0, s0, -8
	s_lshr_b32 s6, s1, 8
	s_lshl_b32 s36, s10, 10
	s_sub_i32 s0, s33, s0
	s_cmp_lt_i32 s0, 0
	s_movk_i32 s38, 0x1b9
	s_cselect_b32 s3, s38, 0x1b8
	s_mul_i32 s0, s3, s0
	s_add_i32 s0, s0, s2
	s_mul_hi_i32 s2, s0, 0x2e8ba2e9
	s_lshr_b32 s3, s2, 31
	s_ashr_i32 s2, s2, 4
	s_add_i32 s2, s2, s3
	s_mul_i32 s3, s2, 0x58
	s_sub_i32 s3, s0, s3
	s_bfe_i32 s0, s3, 0x80000
	s_bfe_u32 s0, s0, 0x2000d
	s_add_i32 s7, s3, s0
	s_bfe_i32 s0, s7, 0x80000
	s_and_b32 s7, s7, 0xfc
	v_lshlrev_b32_e32 v2, 4, v131
	v_and_b32_e32 v3, 32, v131
	s_sub_i32 s3, s3, s7
	v_bitop3_b32 v10, v2, v3, 48 bitop3:0x6c
	v_and_b32_e32 v11, 64, v131
	s_sext_i32_i8 s3, s3
	s_lshl_b32 s2, s2, 2
	v_add_u32_e32 v13, 0x2000, v2
	v_or_b32_e32 v3, v10, v11
	s_sext_i32_i16 s0, s0
	s_add_i32 s2, s2, s3
	v_lshrrev_b32_e32 v2, 7, v13
	s_movk_i32 s3, 0xf0
	s_lshr_b32 s0, s0, 2
	v_lshl_or_b32 v134, v5, 12, v3
	v_and_or_b32 v5, v2, s3, v12
	s_movk_i32 s3, 0xe0
	v_and_or_b32 v2, v2, s3, v4
	s_ashr_i32 s3, s2, 31
	s_bfe_i64 s[12:13], s[0:1], 0x100000
	s_lshl_b64 s[8:9], s[2:3], 20
	s_lshl_b64 s[12:13], s[12:13], 20
	s_add_u32 s30, s50, s12
	s_addc_u32 s31, s51, s13
	s_add_i32 s39, s36, 0
	s_add_i32 m0, s39, 0x10000
	v_lshl_or_b32 v138, v2, 12, v3
	global_load_lds_dwordx4 v134, s[30:31]
	s_add_i32 m0, s39, 0x12000
	s_add_u32 s12, s30, 0x80000
	global_load_lds_dwordx4 v138, s[30:31]
	s_addc_u32 s13, s31, 0
	s_add_i32 m0, s39, 0x14000
	v_lshl_or_b32 v132, v6, 12, v3
	global_load_lds_dwordx4 v134, s[12:13]
	s_add_i32 m0, s39, 0x16000
	s_add_u32 s28, s4, s8
	s_addc_u32 s29, s5, s9
	s_add_i32 s40, s39, 0x2000
	global_load_lds_dwordx4 v138, s[12:13]
	s_mov_b32 m0, s39
	s_add_u32 s8, s28, 0x80000
	v_lshl_or_b32 v136, v5, 12, v3
	global_load_lds_dwordx4 v132, s[28:29]
	s_mov_b32 m0, s40
	s_addc_u32 s9, s29, 0
	s_add_i32 s41, s39, 0x4000
	global_load_lds_dwordx4 v136, s[28:29]
	s_mov_b32 m0, s41
	s_add_i32 s42, s39, 0x6000
	global_load_lds_dwordx4 v132, s[8:9]
	s_mov_b32 m0, s42
	v_mov_b32_e32 v141, 0
	global_load_lds_dwordx4 v136, s[8:9]
	v_mov_b32_e32 v135, v141
	v_mov_b32_e32 v133, v141
	v_mov_b32_e32 v139, v141
	v_mov_b32_e32 v137, v141
	s_cmp_eq_u32 s6, 1
	s_mov_b32 s7, 0
	v_lshl_add_u64 v[8:9], s[30:31], 0, v[134:135]
	v_lshl_add_u64 v[6:7], s[30:31], 0, v[138:139]
	v_lshl_add_u64 v[2:3], s[28:29], 0, v[132:133]
	s_cselect_b64 s[8:9], -1, 0
	s_cmp_lg_u32 s6, 1
	v_lshl_add_u64 v[4:5], s[28:29], 0, v[136:137]
	s_cbranch_scc1 .LBB0_197
	s_setprio 1
	s_barrier

; #define PG8_STAGE(bufoff, gbase, voff) do { _Pragma("unroll") for (int _i = 0; _i < 2; ++_i) \
;         __builtin_amdgcn_global_load_lds((const unsigned*)((const char*)(gbase) + (voff)[_i]), (PG8_LAS unsigned*)(lds + (bufoff) + ldsw + _i * 8192), 16, 0, 0); } while (0)
; #define PG8_LDA(dst, b, h) do { _Pragma("unroll") for (int m = 0; m < 4; ++m) _Pragma("unroll") for (int k = 0; k < 2; ++k) dst[m][k] = *(const PG8_LAS bf16x8*)(lds + PG8_SA(b, h) + aoff + m * 2048 + k * 1024); } while (0)
; #define PG8_LDB(dst, b, h) do { _Pragma("unroll") for (int n = 0; n < 2; ++n) _Pragma("unroll") for (int k = 0; k < 2; ++k) dst[n][k] = *(const PG8_LAS bf16x8*)(lds + PG8_SB(b, h) + boff + n * 2048 + k * 1024); } while (0)
; #define PG8_MMA(ai, bj, At, Bt) do { __builtin_amdgcn_s_setprio(1); _Pragma("unroll") for (int m = 0; m < 4; ++m) _Pragma("unroll") for (int n = 0; n < 2; ++n) _Pragma("unroll") for (int k = 0; k < 2; ++k) \
;         acc[ai][bj][m][n] = __builtin_amdgcn_mfma_f32_16x16x32_bf16(Bt[n][k], At[m][k], acc[ai][bj][m][n], 0, 0, 0); __builtin_amdgcn_s_setprio(0); } while (0)
; #define PG8_WAIT_V(n) asm volatile("s_waitcnt vmcnt(" #n ")" ::: "memory")
; #define PG8_WAIT_L(n) asm volatile("s_waitcnt lgkmcnt(" #n ")" ::: "memory")
; #define PG8_BAR __builtin_amdgcn_s_barrier()
; #define PG8_SCHED __builtin_amdgcn_sched_barrier(0)
; template <class Epi, class Sched, bool ALIGN_EPI = false, bool SP2 = false>
; __device__ __forceinline__ void gemm_phase(PG8_LAS unsigned char* lds, const Gemm g, const Sched& S, const Epi& E) {
;     ...
;             PG8_LDB(B0, 0, 0); PG8_LDB(B1, 0, 1); PG8_SCHED; PG8_LDA(At, 0, 0); PG8_STAGE(PG8_SA(1, 1), a1 + hstep, voffA);
;             PG8_WAIT_V(8); PG8_WAIT_L(0); PG8_BAR; PG8_MMA(0, 0, At, B0); PG8_MMA(0, 1, At, B1); PG8_BAR; PG8_SCHED;
;             PG8_LDA(At, 0, 1); PG8_STAGE(PG8_SB(0, 0), b2, voffB); PG8_STAGE(PG8_SB(0, 1), b2 + hstep, voffB); PG8_STAGE(PG8_SA(0, 0), a2, voffA);
;             PG8_WAIT_V(8); PG8_WAIT_L(0); PG8_BAR; PG8_MMA(1, 0, At, B0); PG8_MMA(1, 1, At, B1); PG8_BAR; PG8_SCHED;
.LBB0_203:
	ds_read_b128 v[150:153], v161
	ds_read_b128 v[154:157], v161 offset:1024
	ds_read_b128 v[166:169], v161 offset:2048
	ds_read_b128 v[170:173], v161 offset:3072
	ds_read_b128 v[174:177], v162
	ds_read_b128 v[178:181], v162 offset:1024
	ds_read_b128 v[182:185], v162 offset:2048
	ds_read_b128 v[186:189], v162 offset:3072
	s_add_u32 s30, s28, 0xfff80080
	s_addc_u32 s31, s29, -1
	s_cmp_eq_u32 s83, 28
	s_cselect_b32 s35, s6, s31
	s_cselect_b32 s34, s23, s30
	s_cselect_b32 s31, s21, s82
	s_cselect_b32 s30, s70, s71
	s_add_i32 m0, s39, 0xc000
	ds_read_b128 v[190:193], v163
	ds_read_b128 v[194:197], v163 offset:1024
	ds_read_b128 v[198:201], v163 offset:2048
	ds_read_b128 v[206:209], v163 offset:3072
	ds_read_b128 v[210:213], v163 offset:4096
	ds_read_b128 v[214:217], v163 offset:5120
	ds_read_b128 v[218:221], v163 offset:6144
	ds_read_b128 v[222:225], v163 offset:7168
	global_load_lds_dwordx4 v142, s[28:29]
	s_add_i32 m0, s39, 0xe000
	s_nop 0
	global_load_lds_dwordx4 v144, s[28:29]
	s_waitcnt vmcnt(8)
	s_waitcnt lgkmcnt(0)
	s_barrier
	s_waitcnt lgkmcnt(0)
	v_mfma_f32_16x16x32_bf16 v[126:129], v[150:153], v[190:193], v[126:129]
	v_mfma_f32_16x16x32_bf16 v[122:125], v[166:169], v[190:193], v[122:125]
	v_mfma_f32_16x16x32_bf16 v[110:113], v[150:153], v[198:201], v[110:113]
	v_mfma_f32_16x16x32_bf16 v[106:109], v[166:169], v[198:201], v[106:109]
	v_mfma_f32_16x16x32_bf16 v[94:97], v[150:153], v[210:213], v[94:97]
	v_mfma_f32_16x16x32_bf16 v[90:93], v[166:169], v[210:213], v[90:93]
	v_mfma_f32_16x16x32_bf16 v[78:81], v[150:153], v[218:221], v[78:81]
	v_mfma_f32_16x16x32_bf16 v[74:77], v[166:169], v[218:221], v[74:77]
	v_mfma_f32_16x16x32_bf16 v[126:129], v[154:157], v[194:197], v[126:129]
	v_mfma_f32_16x16x32_bf16 v[122:125], v[170:173], v[194:197], v[122:125]
	v_mfma_f32_16x16x32_bf16 v[110:113], v[154:157], v[206:209], v[110:113]
	v_mfma_f32_16x16x32_bf16 v[106:109], v[170:173], v[206:209], v[106:109]
	v_mfma_f32_16x16x32_bf16 v[94:97], v[154:157], v[214:217], v[94:97]
	v_mfma_f32_16x16x32_bf16 v[90:93], v[170:173], v[214:217], v[90:93]
	v_mfma_f32_16x16x32_bf16 v[78:81], v[154:157], v[222:225], v[78:81]
	v_mfma_f32_16x16x32_bf16 v[74:77], v[170:173], v[222:225], v[74:77]
	v_mfma_f32_16x16x32_bf16 v[118:121], v[174:177], v[190:193], v[118:121]
	v_mfma_f32_16x16x32_bf16 v[114:117], v[182:185], v[190:193], v[114:117]
	v_mfma_f32_16x16x32_bf16 v[102:105], v[174:177], v[198:201], v[102:105]
	v_mfma_f32_16x16x32_bf16 v[98:101], v[182:185], v[198:201], v[98:101]
	v_mfma_f32_16x16x32_bf16 v[86:89], v[174:177], v[210:213], v[86:89]
	v_mfma_f32_16x16x32_bf16 v[82:85], v[182:185], v[210:213], v[82:85]
	v_mfma_f32_16x16x32_bf16 v[70:73], v[174:177], v[218:221], v[70:73]
	v_mfma_f32_16x16x32_bf16 v[66:69], v[182:185], v[218:221], v[66:69]
	v_mfma_f32_16x16x32_bf16 v[118:121], v[178:181], v[194:197], v[118:121]
	v_mfma_f32_16x16x32_bf16 v[114:117], v[186:189], v[194:197], v[114:117]
	v_mfma_f32_16x16x32_bf16 v[102:105], v[178:181], v[206:209], v[102:105]
	v_mfma_f32_16x16x32_bf16 v[98:101], v[186:189], v[206:209], v[98:101]
	v_mfma_f32_16x16x32_bf16 v[86:89], v[178:181], v[214:217], v[86:89]
	v_mfma_f32_16x16x32_bf16 v[82:85], v[186:189], v[214:217], v[82:85]
	v_mfma_f32_16x16x32_bf16 v[70:73], v[178:181], v[222:225], v[70:73]
	v_mfma_f32_16x16x32_bf16 v[66:69], v[186:189], v[222:225], v[66:69]
	s_barrier
	s_add_i32 s84, s79, s36
	s_add_u32 s64, s30, 0x80
	s_addc_u32 s65, s31, 0
	s_mov_b32 m0, s84
	ds_read_b128 v[190:193], v163 offset:16384
	ds_read_b128 v[194:197], v163 offset:17408
	ds_read_b128 v[198:201], v163 offset:18432
	ds_read_b128 v[206:209], v163 offset:19456
	ds_read_b128 v[210:213], v163 offset:20480
	ds_read_b128 v[214:217], v163 offset:21504
	ds_read_b128 v[218:221], v163 offset:22528
	ds_read_b128 v[222:225], v163 offset:23552
	global_load_lds_dwordx4 v134, s[30:31]
	s_add_i32 m0, s84, 0x2000
	s_add_u32 s84, s30, 0x80000
	s_addc_u32 s85, s31, 0
	s_add_i32 s86, s80, s36
	global_load_lds_dwordx4 v138, s[30:31]
	s_mov_b32 m0, s86
	s_add_u32 s66, s34, 0x80
	s_addc_u32 s67, s35, 0
	global_load_lds_dwordx4 v134, s[84:85]
	s_add_i32 m0, s86, 0x2000
	s_nop 0
	global_load_lds_dwordx4 v138, s[84:85]
	s_mov_b32 m0, s39
	s_nop 0
	global_load_lds_dwordx4 v132, s[34:35]
	s_mov_b32 m0, s40
	s_nop 0
	global_load_lds_dwordx4 v136, s[34:35]
	s_waitcnt vmcnt(8)
	s_waitcnt lgkmcnt(0)
	s_barrier
	s_waitcnt lgkmcnt(0)
	v_mfma_f32_16x16x32_bf16 v[62:65], v[150:153], v[190:193], v[62:65]
	v_mfma_f32_16x16x32_bf16 v[58:61], v[166:169], v[190:193], v[58:61]
	v_mfma_f32_16x16x32_bf16 v[46:49], v[150:153], v[198:201], v[46:49]
	v_mfma_f32_16x16x32_bf16 v[42:45], v[166:169], v[198:201], v[42:45]
	v_mfma_f32_16x16x32_bf16 v[30:33], v[150:153], v[210:213], v[30:33]
	v_mfma_f32_16x16x32_bf16 v[26:29], v[166:169], v[210:213], v[26:29]
	v_mfma_f32_16x16x32_bf16 v[14:17], v[150:153], v[218:221], v[14:17]
	v_mfma_f32_16x16x32_bf16 v[10:13], v[166:169], v[218:221], v[10:13]
	v_mfma_f32_16x16x32_bf16 v[62:65], v[154:157], v[194:197], v[62:65]
	v_mfma_f32_16x16x32_bf16 v[58:61], v[170:173], v[194:197], v[58:61]
	v_mfma_f32_16x16x32_bf16 v[46:49], v[154:157], v[206:209], v[46:49]
	v_mfma_f32_16x16x32_bf16 v[42:45], v[170:173], v[206:209], v[42:45]
	v_mfma_f32_16x16x32_bf16 v[30:33], v[154:157], v[214:217], v[30:33]
	v_mfma_f32_16x16x32_bf16 v[26:29], v[170:173], v[214:217], v[26:29]
	v_mfma_f32_16x16x32_bf16 v[14:17], v[154:157], v[222:225], v[14:17]
	v_mfma_f32_16x16x32_bf16 v[10:13], v[170:173], v[222:225], v[10:13]
	v_mfma_f32_16x16x32_bf16 v[54:57], v[174:177], v[190:193], v[54:57]
	v_mfma_f32_16x16x32_bf16 v[50:53], v[182:185], v[190:193], v[50:53]
	v_mfma_f32_16x16x32_bf16 v[38:41], v[174:177], v[198:201], v[38:41]
	v_mfma_f32_16x16x32_bf16 v[34:37], v[182:185], v[198:201], v[34:37]
	v_mfma_f32_16x16x32_bf16 v[22:25], v[174:177], v[210:213], v[22:25]
	v_mfma_f32_16x16x32_bf16 v[18:21], v[182:185], v[210:213], v[18:21]
	v_mfma_f32_16x16x32_bf16 v[6:9], v[174:177], v[218:221], v[6:9]
	v_mfma_f32_16x16x32_bf16 v[2:5], v[182:185], v[218:221], v[2:5]
	v_mfma_f32_16x16x32_bf16 v[54:57], v[178:181], v[194:197], v[54:57]
	v_mfma_f32_16x16x32_bf16 v[50:53], v[186:189], v[194:197], v[50:53]
	v_mfma_f32_16x16x32_bf16 v[38:41], v[178:181], v[206:209], v[38:41]
	v_mfma_f32_16x16x32_bf16 v[34:37], v[186:189], v[206:209], v[34:37]
	v_mfma_f32_16x16x32_bf16 v[22:25], v[178:181], v[214:217], v[22:25]
	v_mfma_f32_16x16x32_bf16 v[18:21], v[186:189], v[214:217], v[18:21]
	v_mfma_f32_16x16x32_bf16 v[6:9], v[178:181], v[222:225], v[6:9]
	v_mfma_f32_16x16x32_bf16 v[2:5], v[186:189], v[222:225], v[2:5]
	s_barrier
; #define PG8_STAGE(bufoff, gbase, voff) do { _Pragma("unroll") for (int _i = 0; _i < 2; ++_i) \
;         __builtin_amdgcn_global_load_lds((const unsigned*)((const char*)(gbase) + (voff)[_i]), (PG8_LAS unsigned*)(lds + (bufoff) + ldsw + _i * 8192), 16, 0, 0); } while (0)
; #define PG8_LDA(dst, b, h) do { _Pragma("unroll") for (int m = 0; m < 4; ++m) _Pragma("unroll") for (int k = 0; k < 2; ++k) dst[m][k] = *(const PG8_LAS bf16x8*)(lds + PG8_SA(b, h) + aoff + m * 2048 + k * 1024); } while (0)
; #define PG8_LDB(dst, b, h) do { _Pragma("unroll") for (int n = 0; n < 2; ++n) _Pragma("unroll") for (int k = 0; k < 2; ++k) dst[n][k] = *(const PG8_LAS bf16x8*)(lds + PG8_SB(b, h) + boff + n * 2048 + k * 1024); } while (0)
; #define PG8_MMA(ai, bj, At, Bt) do { __builtin_amdgcn_s_setprio(1); _Pragma("unroll") for (int m = 0; m < 4; ++m) _Pragma("unroll") for (int n = 0; n < 2; ++n) _Pragma("unroll") for (int k = 0; k < 2; ++k) \
;         acc[ai][bj][m][n] = __builtin_amdgcn_mfma_f32_16x16x32_bf16(Bt[n][k], At[m][k], acc[ai][bj][m][n], 0, 0, 0); __builtin_amdgcn_s_setprio(0); } while (0)
; #define PG8_WAIT_V(n) asm volatile("s_waitcnt vmcnt(" #n ")" ::: "memory")
; #define PG8_WAIT_L(n) asm volatile("s_waitcnt lgkmcnt(" #n ")" ::: "memory")
; #define PG8_BAR __builtin_amdgcn_s_barrier()
; #define PG8_SCHED __builtin_amdgcn_sched_barrier(0)
; template <class Epi, class Sched, bool ALIGN_EPI = false, bool SP2 = false>
; __device__ __forceinline__ void gemm_phase(PG8_LAS unsigned char* lds, const Gemm g, const Sched& S, const Epi& E) {
;     ...
;         for (int t = 0; t < nt; t += 2) {
;     ...
;             PG8_LDB(B0, 1, 0); PG8_LDB(B1, 1, 1); PG8_SCHED; PG8_LDA(At, 1, 0); PG8_STAGE(PG8_SA(0, 1), a2 + hstep, voffA);
;             PG8_WAIT_V(8); PG8_WAIT_L(0); PG8_BAR; PG8_MMA(0, 0, At, B0); PG8_MMA(0, 1, At, B1); PG8_BAR; PG8_SCHED;
;             PG8_LDA(At, 1, 1); PG8_STAGE(PG8_SB(1, 0), b3, voffB); PG8_STAGE(PG8_SB(1, 1), b3 + hstep, voffB); PG8_STAGE(PG8_SA(1, 0), a3, voffA);
;             PG8_WAIT_V(8); PG8_WAIT_L(0); PG8_BAR; PG8_MMA(1, 0, At, B0); PG8_MMA(1, 1, At, B1); PG8_BAR; PG8_SCHED;
	s_add_i32 s84, 0, 0x18000
	v_add_u32_e32 v140, s84, v159
	s_add_i32 s85, 0, 0x1c000
	ds_read_b128 v[150:153], v140
	ds_read_b128 v[154:157], v140 offset:1024
	ds_read_b128 v[166:169], v140 offset:2048
	ds_read_b128 v[170:173], v140 offset:3072
	v_add_u32_e32 v140, s85, v159
	ds_read_b128 v[174:177], v140
	ds_read_b128 v[178:181], v140 offset:1024
	ds_read_b128 v[182:185], v140 offset:2048
	ds_read_b128 v[186:189], v140 offset:3072
	s_add_u32 s34, s34, 0x80000
	s_addc_u32 s35, s35, 0
	s_mov_b32 m0, s41
	ds_read_b128 v[190:193], v163 offset:32768
	ds_read_b128 v[194:197], v163 offset:33792
	ds_read_b128 v[198:201], v163 offset:34816
	ds_read_b128 v[206:209], v163 offset:35840
	ds_read_b128 v[210:213], v163 offset:36864
	ds_read_b128 v[214:217], v163 offset:37888
	ds_read_b128 v[218:221], v163 offset:38912
	ds_read_b128 v[222:225], v163 offset:39936
	global_load_lds_dwordx4 v132, s[34:35]
	s_mov_b32 m0, s42
	s_nop 0
	global_load_lds_dwordx4 v136, s[34:35]
	s_waitcnt vmcnt(8)
	s_waitcnt lgkmcnt(0)
	s_barrier
	s_waitcnt lgkmcnt(0)
	v_mfma_f32_16x16x32_bf16 v[126:129], v[150:153], v[190:193], v[126:129]
	v_mfma_f32_16x16x32_bf16 v[122:125], v[166:169], v[190:193], v[122:125]
	v_mfma_f32_16x16x32_bf16 v[110:113], v[150:153], v[198:201], v[110:113]
	v_mfma_f32_16x16x32_bf16 v[106:109], v[166:169], v[198:201], v[106:109]
	v_mfma_f32_16x16x32_bf16 v[94:97], v[150:153], v[210:213], v[94:97]
	v_mfma_f32_16x16x32_bf16 v[90:93], v[166:169], v[210:213], v[90:93]
	v_mfma_f32_16x16x32_bf16 v[78:81], v[150:153], v[218:221], v[78:81]
	v_mfma_f32_16x16x32_bf16 v[74:77], v[166:169], v[218:221], v[74:77]
	v_mfma_f32_16x16x32_bf16 v[126:129], v[154:157], v[194:197], v[126:129]
	v_mfma_f32_16x16x32_bf16 v[122:125], v[170:173], v[194:197], v[122:125]
	v_mfma_f32_16x16x32_bf16 v[110:113], v[154:157], v[206:209], v[110:113]
	v_mfma_f32_16x16x32_bf16 v[106:109], v[170:173], v[206:209], v[106:109]
	v_mfma_f32_16x16x32_bf16 v[94:97], v[154:157], v[214:217], v[94:97]
	v_mfma_f32_16x16x32_bf16 v[90:93], v[170:173], v[214:217], v[90:93]
	v_mfma_f32_16x16x32_bf16 v[78:81], v[154:157], v[222:225], v[78:81]
	v_mfma_f32_16x16x32_bf16 v[74:77], v[170:173], v[222:225], v[74:77]
	v_mfma_f32_16x16x32_bf16 v[118:121], v[174:177], v[190:193], v[118:121]
	v_mfma_f32_16x16x32_bf16 v[114:117], v[182:185], v[190:193], v[114:117]
	v_mfma_f32_16x16x32_bf16 v[102:105], v[174:177], v[198:201], v[102:105]
	v_mfma_f32_16x16x32_bf16 v[98:101], v[182:185], v[198:201], v[98:101]
	v_mfma_f32_16x16x32_bf16 v[86:89], v[174:177], v[210:213], v[86:89]
	v_mfma_f32_16x16x32_bf16 v[82:85], v[182:185], v[210:213], v[82:85]
	v_mfma_f32_16x16x32_bf16 v[70:73], v[174:177], v[218:221], v[70:73]
	v_mfma_f32_16x16x32_bf16 v[66:69], v[182:185], v[218:221], v[66:69]
	v_mfma_f32_16x16x32_bf16 v[118:121], v[178:181], v[194:197], v[118:121]
	v_mfma_f32_16x16x32_bf16 v[114:117], v[186:189], v[194:197], v[114:117]
	v_mfma_f32_16x16x32_bf16 v[102:105], v[178:181], v[206:209], v[102:105]
	v_mfma_f32_16x16x32_bf16 v[98:101], v[186:189], v[206:209], v[98:101]
	v_mfma_f32_16x16x32_bf16 v[86:89], v[178:181], v[214:217], v[86:89]
	v_mfma_f32_16x16x32_bf16 v[82:85], v[186:189], v[214:217], v[82:85]
	v_mfma_f32_16x16x32_bf16 v[70:73], v[178:181], v[222:225], v[70:73]
	v_mfma_f32_16x16x32_bf16 v[66:69], v[186:189], v[222:225], v[66:69]
	s_barrier
	s_add_i32 s34, s84, s36
	s_mov_b32 m0, s34
	ds_read_b128 v[190:193], v163 offset:49152
	ds_read_b128 v[194:197], v163 offset:50176
	ds_read_b128 v[198:201], v163 offset:51200
	ds_read_b128 v[206:209], v163 offset:52224
	ds_read_b128 v[210:213], v163 offset:53248
	ds_read_b128 v[214:217], v163 offset:54272
	ds_read_b128 v[218:221], v163 offset:55296
	ds_read_b128 v[222:225], v163 offset:56320
	global_load_lds_dwordx4 v134, s[64:65]
	s_add_i32 m0, s34, 0x2000
	s_add_u32 s30, s30, 0x80080
	s_addc_u32 s31, s31, 0
	s_add_i32 s34, s85, s36
	global_load_lds_dwordx4 v138, s[64:65]
	s_mov_b32 m0, s34
	s_nop 0
	global_load_lds_dwordx4 v134, s[30:31]
	s_add_i32 m0, s34, 0x2000
	s_nop 0
	global_load_lds_dwordx4 v138, s[30:31]
	s_mov_b32 m0, s77
	s_nop 0
	global_load_lds_dwordx4 v132, s[66:67]
	s_mov_b32 m0, s78
	s_nop 0
	global_load_lds_dwordx4 v136, s[66:67]
	s_waitcnt vmcnt(8)
	s_waitcnt lgkmcnt(0)
	s_barrier
	s_waitcnt lgkmcnt(0)
	v_mfma_f32_16x16x32_bf16 v[62:65], v[150:153], v[190:193], v[62:65]
	v_mfma_f32_16x16x32_bf16 v[58:61], v[166:169], v[190:193], v[58:61]
	v_mfma_f32_16x16x32_bf16 v[46:49], v[150:153], v[198:201], v[46:49]
	v_mfma_f32_16x16x32_bf16 v[42:45], v[166:169], v[198:201], v[42:45]
	v_mfma_f32_16x16x32_bf16 v[30:33], v[150:153], v[210:213], v[30:33]
	v_mfma_f32_16x16x32_bf16 v[26:29], v[166:169], v[210:213], v[26:29]
	v_mfma_f32_16x16x32_bf16 v[14:17], v[150:153], v[218:221], v[14:17]
	v_mfma_f32_16x16x32_bf16 v[10:13], v[166:169], v[218:221], v[10:13]
	v_mfma_f32_16x16x32_bf16 v[62:65], v[154:157], v[194:197], v[62:65]
	v_mfma_f32_16x16x32_bf16 v[58:61], v[170:173], v[194:197], v[58:61]
	v_mfma_f32_16x16x32_bf16 v[46:49], v[154:157], v[206:209], v[46:49]
	v_mfma_f32_16x16x32_bf16 v[42:45], v[170:173], v[206:209], v[42:45]
	v_mfma_f32_16x16x32_bf16 v[30:33], v[154:157], v[214:217], v[30:33]
	v_mfma_f32_16x16x32_bf16 v[26:29], v[170:173], v[214:217], v[26:29]
	v_mfma_f32_16x16x32_bf16 v[14:17], v[154:157], v[222:225], v[14:17]
	v_mfma_f32_16x16x32_bf16 v[10:13], v[170:173], v[222:225], v[10:13]
	v_mfma_f32_16x16x32_bf16 v[54:57], v[174:177], v[190:193], v[54:57]
	v_mfma_f32_16x16x32_bf16 v[50:53], v[182:185], v[190:193], v[50:53]
	v_mfma_f32_16x16x32_bf16 v[38:41], v[174:177], v[198:201], v[38:41]
	v_mfma_f32_16x16x32_bf16 v[34:37], v[182:185], v[198:201], v[34:37]
	v_mfma_f32_16x16x32_bf16 v[22:25], v[174:177], v[210:213], v[22:25]
	v_mfma_f32_16x16x32_bf16 v[18:21], v[182:185], v[210:213], v[18:21]
	v_mfma_f32_16x16x32_bf16 v[6:9], v[174:177], v[218:221], v[6:9]
	v_mfma_f32_16x16x32_bf16 v[2:5], v[182:185], v[218:221], v[2:5]
	v_mfma_f32_16x16x32_bf16 v[54:57], v[178:181], v[194:197], v[54:57]
	v_mfma_f32_16x16x32_bf16 v[50:53], v[186:189], v[194:197], v[50:53]
	v_mfma_f32_16x16x32_bf16 v[38:41], v[178:181], v[206:209], v[38:41]
	v_mfma_f32_16x16x32_bf16 v[34:37], v[186:189], v[206:209], v[34:37]
	v_mfma_f32_16x16x32_bf16 v[22:25], v[178:181], v[214:217], v[22:25]
	v_mfma_f32_16x16x32_bf16 v[18:21], v[186:189], v[214:217], v[18:21]
	v_mfma_f32_16x16x32_bf16 v[6:9], v[178:181], v[222:225], v[6:9]
	v_mfma_f32_16x16x32_bf16 v[2:5], v[186:189], v[222:225], v[2:5]
	s_barrier
	s_add_i32 s83, s83, 2
	s_add_u32 s28, s28, 0x100
	s_addc_u32 s29, s29, 0
	s_add_u32 s71, s71, 0x100
	s_addc_u32 s82, s82, 0
	s_cmp_gt_u32 s83, 29
	s_cbranch_scc0 .LBB0_203
	s_and_b64 vcc, exec, s[18:19]
	s_cbranch_vccz .LBB0_206
	s_barrier

; #define PG8_WAIT_V(n) asm volatile("s_waitcnt vmcnt(" #n ")" ::: "memory")
; #define PG8_BAR __builtin_amdgcn_s_barrier()
; template <class Epi, class Sched, bool ALIGN_EPI = false, bool SP2 = false>
; __device__ __forceinline__ void gemm_phase(PG8_LAS unsigned char* lds, const Gemm g, const Sched& S, const Epi& E) {
;     ...
;     PG8_WAIT_V(0);
;     if constexpr (!ALIGN_EPI) { if (wr == 0) PG8_BAR; }
;     PG8_BAR;
.LBB0_281:
	s_waitcnt vmcnt(0)
	s_barrier
	s_setprio 0

; #define PG8_STAGE(bufoff, gbase, voff) do { _Pragma("unroll") for (int _i = 0; _i < 2; ++_i) \
;         __builtin_amdgcn_global_load_lds((const unsigned*)((const char*)(gbase) + (voff)[_i]), (PG8_LAS unsigned*)(lds + (bufoff) + ldsw + _i * 8192), 16, 0, 0); } while (0)
; #define PG8_WAIT_V(n) asm volatile("s_waitcnt vmcnt(" #n ")" ::: "memory")
; #define PG8_BAR __builtin_amdgcn_s_barrier()
; template <class Epi, class Sched, bool ALIGN_EPI = false, bool SP2 = false>
; __device__ __forceinline__ void gemm_phase(PG8_LAS unsigned char* lds, const Gemm g, const Sched& S, const Epi& E) {
;     const int tid = threadIdx.x, wid = __builtin_amdgcn_readfirstlane(tid >> 6), lane = tid & 63, wr = wid >> 2, wc = wid & 3, fr = lane & 15, fq = lane >> 4;
;     const int K = g.K, nt = K / BK;
;     unsigned voffA[2], voffB[2];
; #pragma unroll
;     for (int i = 0; i < 2; ++i) { int R, C; stage_rc(tid * 16 + i * 8192, R, C); const int Rb = Epi::PERM ? ((R & ~31) + perm32(R & 31)) : R;
;         voffA[i] = (unsigned)(R * K + C) * 2u; voffB[i] = (unsigned)(Rb * K + C) * 2u; }
;     ...
;     const char* cA = (const char*)g.A + (size_t)cur.pm * tstep; const char* cB = (const char*)g.Bt + (size_t)cur.pn * tstep;
;     S.a_ready(cur);
;     if constexpr (SP2) {
;         PG8_STAGE(PG8_SB(0, 0), cB, voffB); PG8_STAGE(PG8_SB(0, 1), cB + hstep, voffB); PG8_STAGE(PG8_SA(0, 0), cA, voffA); PG8_STAGE(PG8_SA(0, 1), cA + hstep, voffA);
;         if (wr == 1) PG8_BAR;
;         PG8_WAIT_V(2); PG8_BAR;
;         PG8_STAGE(PG8_SB(1, 0), cB + kstep, voffB); PG8_STAGE(PG8_SA(1, 0), cA + kstep, voffA); PG8_STAGE(PG8_SB(1, 1), cB + hstep + kstep, voffB);
;         PG8_WAIT_V(6); PG8_BAR;
;     } else {
;         PG8_STAGE(PG8_SB(0, 0), cB, voffB); PG8_STAGE(PG8_SA(0, 0), cA, voffA); PG8_STAGE(PG8_SB(0, 1), cB + hstep, voffB); PG8_STAGE(PG8_SA(0, 1), cA + hstep, voffA);
;         if (wr == 1) PG8_BAR;
.LBB0_605:
	s_cmp_lt_i32 s72, 6
	s_cselect_b64 s[0:1], -1, 0
	s_cmp_gt_i32 s73, 5
	s_cselect_b64 s[2:3], -1, 0
	s_and_b64 s[0:1], s[0:1], s[2:3]
	s_andn2_b64 vcc, exec, s[0:1]
	s_cbranch_vccnz .LBB0_688
	v_and_b32_e32 v147, 0x3ff, v0
	s_cmpk_gt_i32 s33, 0x4ff
	v_readfirstlane_b32 s2, v147
	s_cbranch_scc1 .LBB0_638
	v_lshrrev_b32_e32 v4, 1, v147
	v_lshrrev_b32_e32 v5, 5, v147
	v_and_b32_e32 v4, 24, v4
	v_and_b32_e32 v5, 4, v5
	v_bfe_u32 v6, v147, 2, 2
	s_add_u32 s28, s50, 0x2c40000
	v_lshlrev_b32_e32 v2, 4, v147
	v_and_b32_e32 v3, 32, v147
	v_bfe_u32 v12, v147, 2, 4
	v_or3_b32 v4, v5, v6, v4
	v_lshrrev_b32_e32 v5, 3, v147
	s_movk_i32 s0, 0x70
	s_addc_u32 s29, s51, 0
	v_bitop3_b32 v10, v2, v3, 48 bitop3:0x6c
	v_and_b32_e32 v11, 64, v147
	v_and_or_b32 v6, v5, s0, v12
	s_movk_i32 s0, 0x60
	v_add_u32_e32 v13, 0x2000, v2
	s_add_u32 s30, s50, 0x1f940000
	v_or_b32_e32 v3, v10, v11
	v_and_or_b32 v5, v5, s0, v4
	v_lshrrev_b32_e32 v2, 7, v13
	s_movk_i32 s0, 0xf0
	s_addc_u32 s31, s51, 0
	v_lshl_or_b32 v132, v5, 12, v3
	v_and_or_b32 v5, v2, s0, v12
	s_movk_i32 s0, 0xe0
	s_ashr_i32 s34, s33, 31
	v_and_or_b32 v2, v2, s0, v4
	s_lshr_b32 s0, s34, 29
	s_add_i32 s0, s33, s0
	s_ashr_i32 s1, s0, 3
	s_and_b32 s0, s0, -8
	s_sub_i32 s0, s33, s0
	s_cmp_lt_i32 s0, 0
	s_movk_i32 s35, 0xa1
	s_cselect_b32 s3, s35, 0xa0
	s_mul_i32 s0, s3, s0
	s_add_i32 s0, s0, s1
	s_ashr_i32 s1, s0, 31
	s_lshr_b32 s1, s1, 27
	s_add_i32 s1, s0, s1
	s_ashr_i32 s3, s1, 5
	s_andn2_b32 s1, s1, 31
	s_sub_i32 s1, s0, s1
	s_bfe_i32 s0, s1, 0x80000
	s_bfe_u32 s0, s0, 0x2000d
	s_add_i32 s4, s1, s0
	s_bfe_i32 s0, s4, 0x80000
	s_and_b32 s4, s4, 0xfc
	s_sub_i32 s1, s1, s4
	s_lshl_b32 s3, s3, 2
	s_sext_i32_i16 s0, s0
	s_sext_i32_i8 s1, s1
	s_lshr_b32 s0, s0, 2
	s_add_i32 s4, s3, s1
	s_lshr_b32 s1, s2, 6
	s_ashr_i32 s5, s4, 31
	s_bfe_i64 s[8:9], s[0:1], 0x100000
	s_lshr_b32 s3, s2, 8
	s_lshl_b32 s36, s1, 10
	s_lshl_b64 s[6:7], s[4:5], 20
	s_lshl_b64 s[8:9], s[8:9], 20
	s_add_u32 s24, s28, s8
	s_addc_u32 s25, s29, s9
	s_add_i32 s37, s36, 0
	s_add_i32 m0, s37, 0x10000
	v_lshl_or_b32 v136, v2, 12, v3
	global_load_lds_dwordx4 v132, s[24:25]
	s_add_i32 m0, s37, 0x12000
	s_add_u32 s8, s24, 0x80000
	global_load_lds_dwordx4 v136, s[24:25]
	s_addc_u32 s9, s25, 0
	s_add_i32 m0, s37, 0x14000
	v_lshl_or_b32 v130, v6, 12, v3
	global_load_lds_dwordx4 v132, s[8:9]
	s_add_i32 m0, s37, 0x16000
	s_add_u32 s22, s30, s6
	s_addc_u32 s23, s31, s7
	s_add_i32 s38, s37, 0x2000
	global_load_lds_dwordx4 v136, s[8:9]
	s_mov_b32 m0, s37
	s_add_u32 s6, s22, 0x80000
	v_lshl_or_b32 v134, v5, 12, v3
	global_load_lds_dwordx4 v130, s[22:23]
	s_mov_b32 m0, s38
	s_addc_u32 s7, s23, 0
	s_add_i32 s39, s37, 0x4000
	global_load_lds_dwordx4 v134, s[22:23]
	s_mov_b32 m0, s39
	s_add_i32 s40, s37, 0x6000
	global_load_lds_dwordx4 v130, s[6:7]
	s_mov_b32 m0, s40
	v_mov_b32_e32 v133, 0
	global_load_lds_dwordx4 v134, s[6:7]
	v_mov_b32_e32 v137, v133
	v_mov_b32_e32 v131, v133
	v_mov_b32_e32 v135, v133
	s_cmp_eq_u32 s3, 1
	s_mov_b32 s5, 0
	v_lshl_add_u64 v[8:9], s[24:25], 0, v[132:133]
	v_lshl_add_u64 v[6:7], s[24:25], 0, v[136:137]
	v_lshl_add_u64 v[2:3], s[22:23], 0, v[130:131]
	s_cselect_b64 s[6:7], -1, 0
	s_cmp_lg_u32 s3, 1
	v_lshl_add_u64 v[4:5], s[22:23], 0, v[134:135]
	s_cbranch_scc1 .LBB0_609
	s_setprio 1
	s_barrier

; #define PG8_STAGE(bufoff, gbase, voff) do { _Pragma("unroll") for (int _i = 0; _i < 2; ++_i) \
;         __builtin_amdgcn_global_load_lds((const unsigned*)((const char*)(gbase) + (voff)[_i]), (PG8_LAS unsigned*)(lds + (bufoff) + ldsw + _i * 8192), 16, 0, 0); } while (0)
; #define PG8_LDA(dst, b, h) do { _Pragma("unroll") for (int m = 0; m < 4; ++m) _Pragma("unroll") for (int k = 0; k < 2; ++k) dst[m][k] = *(const PG8_LAS bf16x8*)(lds + PG8_SA(b, h) + aoff + m * 2048 + k * 1024); } while (0)
; #define PG8_LDB(dst, b, h) do { _Pragma("unroll") for (int n = 0; n < 2; ++n) _Pragma("unroll") for (int k = 0; k < 2; ++k) dst[n][k] = *(const PG8_LAS bf16x8*)(lds + PG8_SB(b, h) + boff + n * 2048 + k * 1024); } while (0)
; #define PG8_MMA(ai, bj, At, Bt) do { __builtin_amdgcn_s_setprio(1); _Pragma("unroll") for (int m = 0; m < 4; ++m) _Pragma("unroll") for (int n = 0; n < 2; ++n) _Pragma("unroll") for (int k = 0; k < 2; ++k) \
;         acc[ai][bj][m][n] = __builtin_amdgcn_mfma_f32_16x16x32_bf16(Bt[n][k], At[m][k], acc[ai][bj][m][n], 0, 0, 0); __builtin_amdgcn_s_setprio(0); } while (0)
; #define PG8_WAIT_V(n) asm volatile("s_waitcnt vmcnt(" #n ")" ::: "memory")
; #define PG8_WAIT_L(n) asm volatile("s_waitcnt lgkmcnt(" #n ")" ::: "memory")
; #define PG8_BAR __builtin_amdgcn_s_barrier()
; #define PG8_SCHED __builtin_amdgcn_sched_barrier(0)
; template <class Epi, class Sched, bool ALIGN_EPI = false, bool SP2 = false>
; __device__ __forceinline__ void gemm_phase(PG8_LAS unsigned char* lds, const Gemm g, const Sched& S, const Epi& E) {
;     ...
;             PG8_LDB(B0, 0, 0); PG8_LDB(B1, 0, 1); PG8_SCHED; PG8_LDA(At, 0, 0); PG8_STAGE(PG8_SA(1, 1), a1 + hstep, voffA);
;             PG8_WAIT_V(8); PG8_WAIT_L(0); PG8_BAR; PG8_MMA(0, 0, At, B0); PG8_MMA(0, 1, At, B1); PG8_BAR; PG8_SCHED;
;             PG8_LDA(At, 0, 1); PG8_STAGE(PG8_SB(0, 0), b2, voffB); PG8_STAGE(PG8_SB(0, 1), b2 + hstep, voffB); PG8_STAGE(PG8_SA(0, 0), a2, voffA);
;             PG8_WAIT_V(8); PG8_WAIT_L(0); PG8_BAR; PG8_MMA(1, 0, At, B0); PG8_MMA(1, 1, At, B1); PG8_BAR; PG8_SCHED;
.LBB0_615:
	ds_read_b128 v[148:151], v155
	ds_read_b128 v[164:167], v155 offset:1024
	ds_read_b128 v[168:171], v155 offset:2048
	ds_read_b128 v[172:175], v155 offset:3072
	ds_read_b128 v[176:179], v156
	ds_read_b128 v[180:183], v156 offset:1024
	ds_read_b128 v[184:187], v156 offset:2048
	ds_read_b128 v[188:191], v156 offset:3072
	s_add_u32 s24, s22, 0xfff80080
	s_addc_u32 s25, s23, -1
	s_cmp_eq_u32 s79, 28
	s_cselect_b32 s27, s17, s25
	s_cselect_b32 s26, s75, s24
	s_cselect_b32 s25, s15, s78
	s_cselect_b32 s24, s76, s77
	s_add_i32 m0, s37, 0xc000
	ds_read_b128 v[192:195], v157
	ds_read_b128 v[196:199], v157 offset:1024
	ds_read_b128 v[206:209], v157 offset:2048
	ds_read_b128 v[210:213], v157 offset:3072
	ds_read_b128 v[214:217], v157 offset:4096
	ds_read_b128 v[218:221], v157 offset:5120
	ds_read_b128 v[222:225], v157 offset:6144
	ds_read_b128 v[226:229], v157 offset:7168
	global_load_lds_dwordx4 v138, s[22:23]
	s_add_i32 m0, s37, 0xe000
	s_nop 0
	global_load_lds_dwordx4 v140, s[22:23]
	s_waitcnt vmcnt(8)
	s_waitcnt lgkmcnt(0)
	s_barrier
	s_waitcnt lgkmcnt(0)
	v_mfma_f32_16x16x32_bf16 v[126:129], v[148:151], v[192:195], v[126:129]
	v_mfma_f32_16x16x32_bf16 v[122:125], v[168:171], v[192:195], v[122:125]
	v_mfma_f32_16x16x32_bf16 v[110:113], v[148:151], v[206:209], v[110:113]
	v_mfma_f32_16x16x32_bf16 v[106:109], v[168:171], v[206:209], v[106:109]
	v_mfma_f32_16x16x32_bf16 v[94:97], v[148:151], v[214:217], v[94:97]
	v_mfma_f32_16x16x32_bf16 v[90:93], v[168:171], v[214:217], v[90:93]
	v_mfma_f32_16x16x32_bf16 v[78:81], v[148:151], v[222:225], v[78:81]
	v_mfma_f32_16x16x32_bf16 v[74:77], v[168:171], v[222:225], v[74:77]
	v_mfma_f32_16x16x32_bf16 v[126:129], v[164:167], v[196:199], v[126:129]
	v_mfma_f32_16x16x32_bf16 v[122:125], v[172:175], v[196:199], v[122:125]
	v_mfma_f32_16x16x32_bf16 v[110:113], v[164:167], v[210:213], v[110:113]
	v_mfma_f32_16x16x32_bf16 v[106:109], v[172:175], v[210:213], v[106:109]
	v_mfma_f32_16x16x32_bf16 v[94:97], v[164:167], v[218:221], v[94:97]
	v_mfma_f32_16x16x32_bf16 v[90:93], v[172:175], v[218:221], v[90:93]
	v_mfma_f32_16x16x32_bf16 v[78:81], v[164:167], v[226:229], v[78:81]
	v_mfma_f32_16x16x32_bf16 v[74:77], v[172:175], v[226:229], v[74:77]
	v_mfma_f32_16x16x32_bf16 v[118:121], v[176:179], v[192:195], v[118:121]
	v_mfma_f32_16x16x32_bf16 v[114:117], v[184:187], v[192:195], v[114:117]
	v_mfma_f32_16x16x32_bf16 v[102:105], v[176:179], v[206:209], v[102:105]
	v_mfma_f32_16x16x32_bf16 v[98:101], v[184:187], v[206:209], v[98:101]
	v_mfma_f32_16x16x32_bf16 v[86:89], v[176:179], v[214:217], v[86:89]
	v_mfma_f32_16x16x32_bf16 v[82:85], v[184:187], v[214:217], v[82:85]
	v_mfma_f32_16x16x32_bf16 v[70:73], v[176:179], v[222:225], v[70:73]
	v_mfma_f32_16x16x32_bf16 v[66:69], v[184:187], v[222:225], v[66:69]
	v_mfma_f32_16x16x32_bf16 v[118:121], v[180:183], v[196:199], v[118:121]
	v_mfma_f32_16x16x32_bf16 v[114:117], v[188:191], v[196:199], v[114:117]
	v_mfma_f32_16x16x32_bf16 v[102:105], v[180:183], v[210:213], v[102:105]
	v_mfma_f32_16x16x32_bf16 v[98:101], v[188:191], v[210:213], v[98:101]
	v_mfma_f32_16x16x32_bf16 v[86:89], v[180:183], v[218:221], v[86:89]
	v_mfma_f32_16x16x32_bf16 v[82:85], v[188:191], v[218:221], v[82:85]
	v_mfma_f32_16x16x32_bf16 v[70:73], v[180:183], v[226:229], v[70:73]
	v_mfma_f32_16x16x32_bf16 v[66:69], v[188:191], v[226:229], v[66:69]
	s_barrier
	s_add_i32 s64, s45, s36
	s_add_u32 s66, s24, 0x80
	s_addc_u32 s67, s25, 0
	s_mov_b32 m0, s64
	ds_read_b128 v[192:195], v157 offset:16384
	ds_read_b128 v[196:199], v157 offset:17408
	ds_read_b128 v[206:209], v157 offset:18432
	ds_read_b128 v[210:213], v157 offset:19456
	ds_read_b128 v[214:217], v157 offset:20480
	ds_read_b128 v[218:221], v157 offset:21504
	ds_read_b128 v[222:225], v157 offset:22528
	ds_read_b128 v[226:229], v157 offset:23552
	global_load_lds_dwordx4 v132, s[24:25]
	s_add_i32 m0, s64, 0x2000
	s_add_u32 s80, s24, 0x80000
	s_addc_u32 s81, s25, 0
	s_add_i32 s64, s70, s36
	global_load_lds_dwordx4 v136, s[24:25]
	s_mov_b32 m0, s64
	s_add_u32 s68, s26, 0x80
	s_addc_u32 s69, s27, 0
	global_load_lds_dwordx4 v132, s[80:81]
	s_add_i32 m0, s64, 0x2000
	s_nop 0
	global_load_lds_dwordx4 v136, s[80:81]
	s_mov_b32 m0, s37
	s_nop 0
	global_load_lds_dwordx4 v130, s[26:27]
	s_mov_b32 m0, s38
	s_nop 0
	global_load_lds_dwordx4 v134, s[26:27]
	s_waitcnt vmcnt(8)
	s_waitcnt lgkmcnt(0)
	s_barrier
	s_waitcnt lgkmcnt(0)
	v_mfma_f32_16x16x32_bf16 v[62:65], v[148:151], v[192:195], v[62:65]
	v_mfma_f32_16x16x32_bf16 v[58:61], v[168:171], v[192:195], v[58:61]
	v_mfma_f32_16x16x32_bf16 v[46:49], v[148:151], v[206:209], v[46:49]
	v_mfma_f32_16x16x32_bf16 v[42:45], v[168:171], v[206:209], v[42:45]
	v_mfma_f32_16x16x32_bf16 v[30:33], v[148:151], v[214:217], v[30:33]
	v_mfma_f32_16x16x32_bf16 v[26:29], v[168:171], v[214:217], v[26:29]
	v_mfma_f32_16x16x32_bf16 v[14:17], v[148:151], v[222:225], v[14:17]
	v_mfma_f32_16x16x32_bf16 v[10:13], v[168:171], v[222:225], v[10:13]
	v_mfma_f32_16x16x32_bf16 v[62:65], v[164:167], v[196:199], v[62:65]
	v_mfma_f32_16x16x32_bf16 v[58:61], v[172:175], v[196:199], v[58:61]
	v_mfma_f32_16x16x32_bf16 v[46:49], v[164:167], v[210:213], v[46:49]
	v_mfma_f32_16x16x32_bf16 v[42:45], v[172:175], v[210:213], v[42:45]
	v_mfma_f32_16x16x32_bf16 v[30:33], v[164:167], v[218:221], v[30:33]
	v_mfma_f32_16x16x32_bf16 v[26:29], v[172:175], v[218:221], v[26:29]
	v_mfma_f32_16x16x32_bf16 v[14:17], v[164:167], v[226:229], v[14:17]
	v_mfma_f32_16x16x32_bf16 v[10:13], v[172:175], v[226:229], v[10:13]
	v_mfma_f32_16x16x32_bf16 v[54:57], v[176:179], v[192:195], v[54:57]
	v_mfma_f32_16x16x32_bf16 v[50:53], v[184:187], v[192:195], v[50:53]
	v_mfma_f32_16x16x32_bf16 v[38:41], v[176:179], v[206:209], v[38:41]
	v_mfma_f32_16x16x32_bf16 v[34:37], v[184:187], v[206:209], v[34:37]
	v_mfma_f32_16x16x32_bf16 v[22:25], v[176:179], v[214:217], v[22:25]
	v_mfma_f32_16x16x32_bf16 v[18:21], v[184:187], v[214:217], v[18:21]
	v_mfma_f32_16x16x32_bf16 v[6:9], v[176:179], v[222:225], v[6:9]
	v_mfma_f32_16x16x32_bf16 v[2:5], v[184:187], v[222:225], v[2:5]
	v_mfma_f32_16x16x32_bf16 v[54:57], v[180:183], v[196:199], v[54:57]
	v_mfma_f32_16x16x32_bf16 v[50:53], v[188:191], v[196:199], v[50:53]
	v_mfma_f32_16x16x32_bf16 v[38:41], v[180:183], v[210:213], v[38:41]
	v_mfma_f32_16x16x32_bf16 v[34:37], v[188:191], v[210:213], v[34:37]
	v_mfma_f32_16x16x32_bf16 v[22:25], v[180:183], v[218:221], v[22:25]
	v_mfma_f32_16x16x32_bf16 v[18:21], v[188:191], v[218:221], v[18:21]
	v_mfma_f32_16x16x32_bf16 v[6:9], v[180:183], v[226:229], v[6:9]
	v_mfma_f32_16x16x32_bf16 v[2:5], v[188:191], v[226:229], v[2:5]
	s_barrier
; #define PG8_STAGE(bufoff, gbase, voff) do { _Pragma("unroll") for (int _i = 0; _i < 2; ++_i) \
;         __builtin_amdgcn_global_load_lds((const unsigned*)((const char*)(gbase) + (voff)[_i]), (PG8_LAS unsigned*)(lds + (bufoff) + ldsw + _i * 8192), 16, 0, 0); } while (0)
; #define PG8_LDA(dst, b, h) do { _Pragma("unroll") for (int m = 0; m < 4; ++m) _Pragma("unroll") for (int k = 0; k < 2; ++k) dst[m][k] = *(const PG8_LAS bf16x8*)(lds + PG8_SA(b, h) + aoff + m * 2048 + k * 1024); } while (0)
; #define PG8_LDB(dst, b, h) do { _Pragma("unroll") for (int n = 0; n < 2; ++n) _Pragma("unroll") for (int k = 0; k < 2; ++k) dst[n][k] = *(const PG8_LAS bf16x8*)(lds + PG8_SB(b, h) + boff + n * 2048 + k * 1024); } while (0)
; #define PG8_MMA(ai, bj, At, Bt) do { __builtin_amdgcn_s_setprio(1); _Pragma("unroll") for (int m = 0; m < 4; ++m) _Pragma("unroll") for (int n = 0; n < 2; ++n) _Pragma("unroll") for (int k = 0; k < 2; ++k) \
;         acc[ai][bj][m][n] = __builtin_amdgcn_mfma_f32_16x16x32_bf16(Bt[n][k], At[m][k], acc[ai][bj][m][n], 0, 0, 0); __builtin_amdgcn_s_setprio(0); } while (0)
; #define PG8_WAIT_V(n) asm volatile("s_waitcnt vmcnt(" #n ")" ::: "memory")
; #define PG8_WAIT_L(n) asm volatile("s_waitcnt lgkmcnt(" #n ")" ::: "memory")
; #define PG8_BAR __builtin_amdgcn_s_barrier()
; #define PG8_SCHED __builtin_amdgcn_sched_barrier(0)
; template <class Epi, class Sched, bool ALIGN_EPI = false, bool SP2 = false>
; __device__ __forceinline__ void gemm_phase(PG8_LAS unsigned char* lds, const Gemm g, const Sched& S, const Epi& E) {
;     ...
;         for (int t = 0; t < nt; t += 2) {
;     ...
;             PG8_LDB(B0, 1, 0); PG8_LDB(B1, 1, 1); PG8_SCHED; PG8_LDA(At, 1, 0); PG8_STAGE(PG8_SA(0, 1), a2 + hstep, voffA);
;             PG8_WAIT_V(8); PG8_WAIT_L(0); PG8_BAR; PG8_MMA(0, 0, At, B0); PG8_MMA(0, 1, At, B1); PG8_BAR; PG8_SCHED;
;             PG8_LDA(At, 1, 1); PG8_STAGE(PG8_SB(1, 0), b3, voffB); PG8_STAGE(PG8_SB(1, 1), b3 + hstep, voffB); PG8_STAGE(PG8_SA(1, 0), a3, voffA);
;             PG8_WAIT_V(8); PG8_WAIT_L(0); PG8_BAR; PG8_MMA(1, 0, At, B0); PG8_MMA(1, 1, At, B1); PG8_BAR; PG8_SCHED;
	s_add_i32 s64, 0, 0x18000
	v_add_u32_e32 v159, s64, v153
	s_add_i32 s65, 0, 0x1c000
	ds_read_b128 v[148:151], v159
	ds_read_b128 v[164:167], v159 offset:1024
	ds_read_b128 v[168:171], v159 offset:2048
	ds_read_b128 v[172:175], v159 offset:3072
	v_add_u32_e32 v159, s65, v153
	ds_read_b128 v[176:179], v159
	ds_read_b128 v[180:183], v159 offset:1024
	ds_read_b128 v[184:187], v159 offset:2048
	ds_read_b128 v[188:191], v159 offset:3072
	s_add_u32 s26, s26, 0x80000
	s_addc_u32 s27, s27, 0
	s_mov_b32 m0, s39
	ds_read_b128 v[192:195], v157 offset:32768
	ds_read_b128 v[196:199], v157 offset:33792
	ds_read_b128 v[206:209], v157 offset:34816
	ds_read_b128 v[210:213], v157 offset:35840
	ds_read_b128 v[214:217], v157 offset:36864
	ds_read_b128 v[218:221], v157 offset:37888
	ds_read_b128 v[222:225], v157 offset:38912
	ds_read_b128 v[226:229], v157 offset:39936
	global_load_lds_dwordx4 v130, s[26:27]
	s_mov_b32 m0, s40
	s_nop 0
	global_load_lds_dwordx4 v134, s[26:27]
	s_waitcnt vmcnt(8)
	s_waitcnt lgkmcnt(0)
	s_barrier
	s_waitcnt lgkmcnt(0)
	v_mfma_f32_16x16x32_bf16 v[126:129], v[148:151], v[192:195], v[126:129]
	v_mfma_f32_16x16x32_bf16 v[122:125], v[168:171], v[192:195], v[122:125]
	v_mfma_f32_16x16x32_bf16 v[110:113], v[148:151], v[206:209], v[110:113]
	v_mfma_f32_16x16x32_bf16 v[106:109], v[168:171], v[206:209], v[106:109]
	v_mfma_f32_16x16x32_bf16 v[94:97], v[148:151], v[214:217], v[94:97]
	v_mfma_f32_16x16x32_bf16 v[90:93], v[168:171], v[214:217], v[90:93]
	v_mfma_f32_16x16x32_bf16 v[78:81], v[148:151], v[222:225], v[78:81]
	v_mfma_f32_16x16x32_bf16 v[74:77], v[168:171], v[222:225], v[74:77]
	v_mfma_f32_16x16x32_bf16 v[126:129], v[164:167], v[196:199], v[126:129]
	v_mfma_f32_16x16x32_bf16 v[122:125], v[172:175], v[196:199], v[122:125]
	v_mfma_f32_16x16x32_bf16 v[110:113], v[164:167], v[210:213], v[110:113]
	v_mfma_f32_16x16x32_bf16 v[106:109], v[172:175], v[210:213], v[106:109]
	v_mfma_f32_16x16x32_bf16 v[94:97], v[164:167], v[218:221], v[94:97]
	v_mfma_f32_16x16x32_bf16 v[90:93], v[172:175], v[218:221], v[90:93]
	v_mfma_f32_16x16x32_bf16 v[78:81], v[164:167], v[226:229], v[78:81]
	v_mfma_f32_16x16x32_bf16 v[74:77], v[172:175], v[226:229], v[74:77]
	v_mfma_f32_16x16x32_bf16 v[118:121], v[176:179], v[192:195], v[118:121]
	v_mfma_f32_16x16x32_bf16 v[114:117], v[184:187], v[192:195], v[114:117]
	v_mfma_f32_16x16x32_bf16 v[102:105], v[176:179], v[206:209], v[102:105]
	v_mfma_f32_16x16x32_bf16 v[98:101], v[184:187], v[206:209], v[98:101]
	v_mfma_f32_16x16x32_bf16 v[86:89], v[176:179], v[214:217], v[86:89]
	v_mfma_f32_16x16x32_bf16 v[82:85], v[184:187], v[214:217], v[82:85]
	v_mfma_f32_16x16x32_bf16 v[70:73], v[176:179], v[222:225], v[70:73]
	v_mfma_f32_16x16x32_bf16 v[66:69], v[184:187], v[222:225], v[66:69]
	v_mfma_f32_16x16x32_bf16 v[118:121], v[180:183], v[196:199], v[118:121]
	v_mfma_f32_16x16x32_bf16 v[114:117], v[188:191], v[196:199], v[114:117]
	v_mfma_f32_16x16x32_bf16 v[102:105], v[180:183], v[210:213], v[102:105]
	v_mfma_f32_16x16x32_bf16 v[98:101], v[188:191], v[210:213], v[98:101]
	v_mfma_f32_16x16x32_bf16 v[86:89], v[180:183], v[218:221], v[86:89]
	v_mfma_f32_16x16x32_bf16 v[82:85], v[188:191], v[218:221], v[82:85]
	v_mfma_f32_16x16x32_bf16 v[70:73], v[180:183], v[226:229], v[70:73]
	v_mfma_f32_16x16x32_bf16 v[66:69], v[188:191], v[226:229], v[66:69]
	s_barrier
	s_add_i32 s26, s64, s36
	s_mov_b32 m0, s26
	ds_read_b128 v[192:195], v157 offset:49152
	ds_read_b128 v[196:199], v157 offset:50176
	ds_read_b128 v[206:209], v157 offset:51200
	ds_read_b128 v[210:213], v157 offset:52224
	ds_read_b128 v[214:217], v157 offset:53248
	ds_read_b128 v[218:221], v157 offset:54272
	ds_read_b128 v[222:225], v157 offset:55296
	ds_read_b128 v[226:229], v157 offset:56320
	global_load_lds_dwordx4 v132, s[66:67]
	s_add_i32 m0, s26, 0x2000
	s_add_u32 s24, s24, 0x80080
	s_addc_u32 s25, s25, 0
	s_add_i32 s26, s65, s36
	global_load_lds_dwordx4 v136, s[66:67]
	s_mov_b32 m0, s26
	s_nop 0
	global_load_lds_dwordx4 v132, s[24:25]
	s_add_i32 m0, s26, 0x2000
	s_nop 0
	global_load_lds_dwordx4 v136, s[24:25]
	s_mov_b32 m0, s43
	s_nop 0
	global_load_lds_dwordx4 v130, s[68:69]
	s_mov_b32 m0, s44
	s_nop 0
	global_load_lds_dwordx4 v134, s[68:69]
	s_waitcnt vmcnt(8)
	s_waitcnt lgkmcnt(0)
	s_barrier
	s_waitcnt lgkmcnt(0)
	v_mfma_f32_16x16x32_bf16 v[62:65], v[148:151], v[192:195], v[62:65]
	v_mfma_f32_16x16x32_bf16 v[58:61], v[168:171], v[192:195], v[58:61]
	v_mfma_f32_16x16x32_bf16 v[46:49], v[148:151], v[206:209], v[46:49]
	v_mfma_f32_16x16x32_bf16 v[42:45], v[168:171], v[206:209], v[42:45]
	v_mfma_f32_16x16x32_bf16 v[30:33], v[148:151], v[214:217], v[30:33]
	v_mfma_f32_16x16x32_bf16 v[26:29], v[168:171], v[214:217], v[26:29]
	v_mfma_f32_16x16x32_bf16 v[14:17], v[148:151], v[222:225], v[14:17]
	v_mfma_f32_16x16x32_bf16 v[10:13], v[168:171], v[222:225], v[10:13]
	v_mfma_f32_16x16x32_bf16 v[62:65], v[164:167], v[196:199], v[62:65]
	v_mfma_f32_16x16x32_bf16 v[58:61], v[172:175], v[196:199], v[58:61]
	v_mfma_f32_16x16x32_bf16 v[46:49], v[164:167], v[210:213], v[46:49]
	v_mfma_f32_16x16x32_bf16 v[42:45], v[172:175], v[210:213], v[42:45]
	v_mfma_f32_16x16x32_bf16 v[30:33], v[164:167], v[218:221], v[30:33]
	v_mfma_f32_16x16x32_bf16 v[26:29], v[172:175], v[218:221], v[26:29]
	v_mfma_f32_16x16x32_bf16 v[14:17], v[164:167], v[226:229], v[14:17]
	v_mfma_f32_16x16x32_bf16 v[10:13], v[172:175], v[226:229], v[10:13]
	v_mfma_f32_16x16x32_bf16 v[54:57], v[176:179], v[192:195], v[54:57]
	v_mfma_f32_16x16x32_bf16 v[50:53], v[184:187], v[192:195], v[50:53]
	v_mfma_f32_16x16x32_bf16 v[38:41], v[176:179], v[206:209], v[38:41]
	v_mfma_f32_16x16x32_bf16 v[34:37], v[184:187], v[206:209], v[34:37]
	v_mfma_f32_16x16x32_bf16 v[22:25], v[176:179], v[214:217], v[22:25]
	v_mfma_f32_16x16x32_bf16 v[18:21], v[184:187], v[214:217], v[18:21]
	v_mfma_f32_16x16x32_bf16 v[6:9], v[176:179], v[222:225], v[6:9]
	v_mfma_f32_16x16x32_bf16 v[2:5], v[184:187], v[222:225], v[2:5]
	v_mfma_f32_16x16x32_bf16 v[54:57], v[180:183], v[196:199], v[54:57]
	v_mfma_f32_16x16x32_bf16 v[50:53], v[188:191], v[196:199], v[50:53]
	v_mfma_f32_16x16x32_bf16 v[38:41], v[180:183], v[210:213], v[38:41]
	v_mfma_f32_16x16x32_bf16 v[34:37], v[188:191], v[210:213], v[34:37]
	v_mfma_f32_16x16x32_bf16 v[22:25], v[180:183], v[218:221], v[22:25]
	v_mfma_f32_16x16x32_bf16 v[18:21], v[188:191], v[218:221], v[18:21]
	v_mfma_f32_16x16x32_bf16 v[6:9], v[180:183], v[226:229], v[6:9]
	v_mfma_f32_16x16x32_bf16 v[2:5], v[188:191], v[226:229], v[2:5]
	s_barrier
	s_add_i32 s79, s79, 2
	s_add_u32 s22, s22, 0x100
	s_addc_u32 s23, s23, 0
	s_add_u32 s77, s77, 0x100
	s_addc_u32 s78, s78, 0
	s_cmp_gt_u32 s79, 29
	s_cbranch_scc0 .LBB0_615
	s_and_b64 vcc, exec, s[12:13]
	s_cbranch_vccz .LBB0_618
	s_barrier

; #define PG8_STAGE(bufoff, gbase, voff) do { _Pragma("unroll") for (int _i = 0; _i < 2; ++_i) \
;         __builtin_amdgcn_global_load_lds((const unsigned*)((const char*)(gbase) + (voff)[_i]), (PG8_LAS unsigned*)(lds + (bufoff) + ldsw + _i * 8192), 16, 0, 0); } while (0)
; #define PG8_WAIT_V(n) asm volatile("s_waitcnt vmcnt(" #n ")" ::: "memory")
; #define PG8_BAR __builtin_amdgcn_s_barrier()
; template <class Epi, class Sched, bool ALIGN_EPI = false, bool SP2 = false>
; __device__ __forceinline__ void gemm_phase(PG8_LAS unsigned char* lds, const Gemm g, const Sched& S, const Epi& E) {
;     const int tid = threadIdx.x, wid = __builtin_amdgcn_readfirstlane(tid >> 6), lane = tid & 63, wr = wid >> 2, wc = wid & 3, fr = lane & 15, fq = lane >> 4;
;     const int K = g.K, nt = K / BK;
;     unsigned voffA[2], voffB[2];
; #pragma unroll
;     for (int i = 0; i < 2; ++i) { int R, C; stage_rc(tid * 16 + i * 8192, R, C); const int Rb = Epi::PERM ? ((R & ~31) + perm32(R & 31)) : R;
;         voffA[i] = (unsigned)(R * K + C) * 2u; voffB[i] = (unsigned)(Rb * K + C) * 2u; }
;     ...
;     const char* cA = (const char*)g.A + (size_t)cur.pm * tstep; const char* cB = (const char*)g.Bt + (size_t)cur.pn * tstep;
;     S.a_ready(cur);
;     if constexpr (SP2) {
;         PG8_STAGE(PG8_SB(0, 0), cB, voffB); PG8_STAGE(PG8_SB(0, 1), cB + hstep, voffB); PG8_STAGE(PG8_SA(0, 0), cA, voffA); PG8_STAGE(PG8_SA(0, 1), cA + hstep, voffA);
;         if (wr == 1) PG8_BAR;
;         PG8_WAIT_V(2); PG8_BAR;
;         PG8_STAGE(PG8_SB(1, 0), cB + kstep, voffB); PG8_STAGE(PG8_SA(1, 0), cA + kstep, voffA); PG8_STAGE(PG8_SB(1, 1), cB + hstep + kstep, voffB);
;         PG8_WAIT_V(6); PG8_BAR;
;     } else {
;         PG8_STAGE(PG8_SB(0, 0), cB, voffB); PG8_STAGE(PG8_SA(0, 0), cA, voffA); PG8_STAGE(PG8_SB(0, 1), cB + hstep, voffB); PG8_STAGE(PG8_SA(0, 1), cA + hstep, voffA);
;         if (wr == 1) PG8_BAR;
.LBB0_756:
	s_or_b64 exec, exec, s[0:1]
	s_cmpk_gt_i32 s33, 0xdbf
	v_readfirstlane_b32 s1, v131
	s_barrier
	s_cbranch_scc1 .LBB0_844
	v_lshrrev_b32_e32 v4, 1, v131
	v_and_b32_e32 v130, 24, v4
	v_and_b32_e32 v4, 4, v94
	v_bfe_u32 v5, v131, 2, 2
	v_bfe_u32 v12, v131, 2, 4
	v_or3_b32 v4, v4, v5, v130
	v_lshrrev_b32_e32 v5, 3, v131
	s_movk_i32 s0, 0x70
	v_and_or_b32 v6, v5, s0, v12
	s_movk_i32 s0, 0x60
	s_ashr_i32 s37, s33, 31
	v_and_or_b32 v5, v5, s0, v4
	s_lshr_b32 s0, s37, 29
	s_add_i32 s0, s33, s0
	s_lshr_b32 s10, s1, 6
	s_ashr_i32 s2, s0, 3
	s_and_b32 s0, s0, -8
	s_lshr_b32 s6, s1, 8
	s_lshl_b32 s36, s10, 10
	s_sub_i32 s0, s33, s0
	s_cmp_lt_i32 s0, 0
	s_movk_i32 s38, 0x1b9
	s_cselect_b32 s3, s38, 0x1b8
	s_mul_i32 s0, s3, s0
	s_add_i32 s0, s0, s2
	s_mul_hi_i32 s2, s0, 0x2e8ba2e9
	s_lshr_b32 s3, s2, 31
	s_ashr_i32 s2, s2, 4
	s_add_i32 s2, s2, s3
	s_mul_i32 s3, s2, 0x58
	s_sub_i32 s3, s0, s3
	s_bfe_i32 s0, s3, 0x80000
	s_bfe_u32 s0, s0, 0x2000d
	s_add_i32 s7, s3, s0
	s_bfe_i32 s0, s7, 0x80000
	s_sext_i32_i16 s0, s0
	s_and_b32 s7, s7, 0xfc
	s_lshr_b32 s0, s0, 2
	s_sub_i32 s3, s3, s7
	v_lshlrev_b32_e32 v2, 4, v131
	v_and_b32_e32 v3, 32, v131
	s_add_u32 s39, s50, 0x1620000
	v_bitop3_b32 v10, v2, v3, 48 bitop3:0x6c
	v_and_b32_e32 v11, 64, v131
	s_sext_i32_i8 s3, s3
	s_addc_u32 s40, s51, 0
	s_lshl_b32 s2, s2, 2
	v_add_u32_e32 v13, 0x2000, v2
	v_or_b32_e32 v3, v10, v11
	s_add_i32 s2, s2, s3
	v_lshrrev_b32_e32 v2, 7, v13
	s_movk_i32 s3, 0xf0
	v_lshl_or_b32 v134, v5, 12, v3
	v_and_or_b32 v5, v2, s3, v12
	s_movk_i32 s3, 0xe0
	v_and_or_b32 v2, v2, s3, v4
	s_ashr_i32 s3, s2, 31
	s_bfe_i64 s[12:13], s[0:1], 0x100000
	s_lshl_b64 s[8:9], s[2:3], 20
	s_lshl_b64 s[12:13], s[12:13], 20
	s_add_u32 s30, s39, s12
	s_addc_u32 s31, s40, s13
	s_add_i32 s41, s36, 0
	s_add_i32 m0, s41, 0x10000
	v_lshl_or_b32 v138, v2, 12, v3
	global_load_lds_dwordx4 v134, s[30:31]
	s_add_i32 m0, s41, 0x12000
	s_add_u32 s12, s30, 0x80000
	global_load_lds_dwordx4 v138, s[30:31]
	s_addc_u32 s13, s31, 0
	s_add_i32 m0, s41, 0x14000
	v_lshl_or_b32 v132, v6, 12, v3
	global_load_lds_dwordx4 v134, s[12:13]
	s_add_i32 m0, s41, 0x16000
	s_add_u32 s28, s4, s8
	s_addc_u32 s29, s5, s9
	s_add_i32 s42, s41, 0x2000
	global_load_lds_dwordx4 v138, s[12:13]
	s_mov_b32 m0, s41
	s_add_u32 s8, s28, 0x80000
	v_lshl_or_b32 v136, v5, 12, v3
	global_load_lds_dwordx4 v132, s[28:29]
	s_mov_b32 m0, s42
	s_addc_u32 s9, s29, 0
	s_add_i32 s43, s41, 0x4000
	global_load_lds_dwordx4 v136, s[28:29]
	s_mov_b32 m0, s43
	s_add_i32 s44, s41, 0x6000
	global_load_lds_dwordx4 v132, s[8:9]
	s_mov_b32 m0, s44
	v_mov_b32_e32 v141, 0
	global_load_lds_dwordx4 v136, s[8:9]
	v_mov_b32_e32 v135, v141
	v_mov_b32_e32 v133, v141
	v_mov_b32_e32 v139, v141
	v_mov_b32_e32 v137, v141
	s_cmp_eq_u32 s6, 1
	s_mov_b32 s7, 0
	v_lshl_add_u64 v[8:9], s[30:31], 0, v[134:135]
	v_lshl_add_u64 v[6:7], s[30:31], 0, v[138:139]
	v_lshl_add_u64 v[2:3], s[28:29], 0, v[132:133]
	s_cselect_b64 s[8:9], -1, 0
	s_cmp_lg_u32 s6, 1
	v_lshl_add_u64 v[4:5], s[28:29], 0, v[136:137]
	s_cbranch_scc1 .LBB0_759
	s_setprio 1
	s_barrier

; #define PG8_STAGE(bufoff, gbase, voff) do { _Pragma("unroll") for (int _i = 0; _i < 2; ++_i) \
;         __builtin_amdgcn_global_load_lds((const unsigned*)((const char*)(gbase) + (voff)[_i]), (PG8_LAS unsigned*)(lds + (bufoff) + ldsw + _i * 8192), 16, 0, 0); } while (0)
; #define PG8_LDA(dst, b, h) do { _Pragma("unroll") for (int m = 0; m < 4; ++m) _Pragma("unroll") for (int k = 0; k < 2; ++k) dst[m][k] = *(const PG8_LAS bf16x8*)(lds + PG8_SA(b, h) + aoff + m * 2048 + k * 1024); } while (0)
; #define PG8_LDB(dst, b, h) do { _Pragma("unroll") for (int n = 0; n < 2; ++n) _Pragma("unroll") for (int k = 0; k < 2; ++k) dst[n][k] = *(const PG8_LAS bf16x8*)(lds + PG8_SB(b, h) + boff + n * 2048 + k * 1024); } while (0)
; #define PG8_MMA(ai, bj, At, Bt) do { __builtin_amdgcn_s_setprio(1); _Pragma("unroll") for (int m = 0; m < 4; ++m) _Pragma("unroll") for (int n = 0; n < 2; ++n) _Pragma("unroll") for (int k = 0; k < 2; ++k) \
;         acc[ai][bj][m][n] = __builtin_amdgcn_mfma_f32_16x16x32_bf16(Bt[n][k], At[m][k], acc[ai][bj][m][n], 0, 0, 0); __builtin_amdgcn_s_setprio(0); } while (0)
; #define PG8_WAIT_V(n) asm volatile("s_waitcnt vmcnt(" #n ")" ::: "memory")
; #define PG8_WAIT_L(n) asm volatile("s_waitcnt lgkmcnt(" #n ")" ::: "memory")
; #define PG8_BAR __builtin_amdgcn_s_barrier()
; #define PG8_SCHED __builtin_amdgcn_sched_barrier(0)
; template <class Epi, class Sched, bool ALIGN_EPI = false, bool SP2 = false>
; __device__ __forceinline__ void gemm_phase(PG8_LAS unsigned char* lds, const Gemm g, const Sched& S, const Epi& E) {
;     ...
;             PG8_LDB(B0, 0, 0); PG8_LDB(B1, 0, 1); PG8_SCHED; PG8_LDA(At, 0, 0); PG8_STAGE(PG8_SA(1, 1), a1 + hstep, voffA);
;             PG8_WAIT_V(8); PG8_WAIT_L(0); PG8_BAR; PG8_MMA(0, 0, At, B0); PG8_MMA(0, 1, At, B1); PG8_BAR; PG8_SCHED;
;             PG8_LDA(At, 0, 1); PG8_STAGE(PG8_SB(0, 0), b2, voffB); PG8_STAGE(PG8_SB(0, 1), b2 + hstep, voffB); PG8_STAGE(PG8_SA(0, 0), a2, voffA);
;             PG8_WAIT_V(8); PG8_WAIT_L(0); PG8_BAR; PG8_MMA(1, 0, At, B0); PG8_MMA(1, 1, At, B1); PG8_BAR; PG8_SCHED;
.LBB0_765:
	ds_read_b128 v[152:155], v164
	ds_read_b128 v[156:159], v164 offset:1024
	ds_read_b128 v[170:173], v164 offset:2048
	ds_read_b128 v[174:177], v164 offset:3072
	ds_read_b128 v[178:181], v165
	ds_read_b128 v[182:185], v165 offset:1024
	ds_read_b128 v[186:189], v165 offset:2048
	ds_read_b128 v[190:193], v165 offset:3072
	s_add_u32 s30, s28, 0xfff80080
	s_addc_u32 s31, s29, -1
	s_cmp_eq_u32 s85, 28
	s_cselect_b32 s35, s6, s31
	s_cselect_b32 s34, s23, s30
	s_cselect_b32 s31, s21, s84
	s_cselect_b32 s30, s70, s71
	s_add_i32 m0, s41, 0xc000
	ds_read_b128 v[194:197], v166
	ds_read_b128 v[204:207], v166 offset:1024
	ds_read_b128 v[208:211], v166 offset:2048
	ds_read_b128 v[212:215], v166 offset:3072
	ds_read_b128 v[216:219], v166 offset:4096
	ds_read_b128 v[220:223], v166 offset:5120
	ds_read_b128 v[224:227], v166 offset:6144
	ds_read_b128 v[228:231], v166 offset:7168
	global_load_lds_dwordx4 v142, s[28:29]
	s_add_i32 m0, s41, 0xe000
	s_nop 0
	global_load_lds_dwordx4 v144, s[28:29]
	s_waitcnt vmcnt(8)
	s_waitcnt lgkmcnt(0)
	s_barrier
	s_waitcnt lgkmcnt(0)
	v_mfma_f32_16x16x32_bf16 v[126:129], v[152:155], v[194:197], v[126:129]
	v_mfma_f32_16x16x32_bf16 v[122:125], v[170:173], v[194:197], v[122:125]
	v_mfma_f32_16x16x32_bf16 v[110:113], v[152:155], v[208:211], v[110:113]
	v_mfma_f32_16x16x32_bf16 v[106:109], v[170:173], v[208:211], v[106:109]
	v_mfma_f32_16x16x32_bf16 v[94:97], v[152:155], v[216:219], v[94:97]
	v_mfma_f32_16x16x32_bf16 v[90:93], v[170:173], v[216:219], v[90:93]
	v_mfma_f32_16x16x32_bf16 v[78:81], v[152:155], v[224:227], v[78:81]
	v_mfma_f32_16x16x32_bf16 v[74:77], v[170:173], v[224:227], v[74:77]
	v_mfma_f32_16x16x32_bf16 v[126:129], v[156:159], v[204:207], v[126:129]
	v_mfma_f32_16x16x32_bf16 v[122:125], v[174:177], v[204:207], v[122:125]
	v_mfma_f32_16x16x32_bf16 v[110:113], v[156:159], v[212:215], v[110:113]
	v_mfma_f32_16x16x32_bf16 v[106:109], v[174:177], v[212:215], v[106:109]
	v_mfma_f32_16x16x32_bf16 v[94:97], v[156:159], v[220:223], v[94:97]
	v_mfma_f32_16x16x32_bf16 v[90:93], v[174:177], v[220:223], v[90:93]
	v_mfma_f32_16x16x32_bf16 v[78:81], v[156:159], v[228:231], v[78:81]
	v_mfma_f32_16x16x32_bf16 v[74:77], v[174:177], v[228:231], v[74:77]
	v_mfma_f32_16x16x32_bf16 v[118:121], v[178:181], v[194:197], v[118:121]
	v_mfma_f32_16x16x32_bf16 v[114:117], v[186:189], v[194:197], v[114:117]
	v_mfma_f32_16x16x32_bf16 v[102:105], v[178:181], v[208:211], v[102:105]
	v_mfma_f32_16x16x32_bf16 v[98:101], v[186:189], v[208:211], v[98:101]
	v_mfma_f32_16x16x32_bf16 v[86:89], v[178:181], v[216:219], v[86:89]
	v_mfma_f32_16x16x32_bf16 v[82:85], v[186:189], v[216:219], v[82:85]
	v_mfma_f32_16x16x32_bf16 v[70:73], v[178:181], v[224:227], v[70:73]
	v_mfma_f32_16x16x32_bf16 v[66:69], v[186:189], v[224:227], v[66:69]
	v_mfma_f32_16x16x32_bf16 v[118:121], v[182:185], v[204:207], v[118:121]
	v_mfma_f32_16x16x32_bf16 v[114:117], v[190:193], v[204:207], v[114:117]
	v_mfma_f32_16x16x32_bf16 v[102:105], v[182:185], v[212:215], v[102:105]
	v_mfma_f32_16x16x32_bf16 v[98:101], v[190:193], v[212:215], v[98:101]
	v_mfma_f32_16x16x32_bf16 v[86:89], v[182:185], v[220:223], v[86:89]
	v_mfma_f32_16x16x32_bf16 v[82:85], v[190:193], v[220:223], v[82:85]
	v_mfma_f32_16x16x32_bf16 v[70:73], v[182:185], v[228:231], v[70:73]
	v_mfma_f32_16x16x32_bf16 v[66:69], v[190:193], v[228:231], v[66:69]
	s_barrier
	s_add_i32 s64, s81, s36
	s_add_u32 s66, s30, 0x80
	s_addc_u32 s67, s31, 0
	s_mov_b32 m0, s64
	ds_read_b128 v[194:197], v166 offset:16384
	ds_read_b128 v[204:207], v166 offset:17408
	ds_read_b128 v[208:211], v166 offset:18432
	ds_read_b128 v[212:215], v166 offset:19456
	ds_read_b128 v[216:219], v166 offset:20480
	ds_read_b128 v[220:223], v166 offset:21504
	ds_read_b128 v[224:227], v166 offset:22528
	ds_read_b128 v[228:231], v166 offset:23552
	global_load_lds_dwordx4 v134, s[30:31]
	s_add_i32 m0, s64, 0x2000
	s_add_u32 s86, s30, 0x80000
	s_addc_u32 s87, s31, 0
	s_add_i32 s64, s82, s36
	global_load_lds_dwordx4 v138, s[30:31]
	s_mov_b32 m0, s64
	s_add_u32 s68, s34, 0x80
	s_addc_u32 s69, s35, 0
	global_load_lds_dwordx4 v134, s[86:87]
	s_add_i32 m0, s64, 0x2000
	s_nop 0
	global_load_lds_dwordx4 v138, s[86:87]
	s_mov_b32 m0, s41
	s_nop 0
	global_load_lds_dwordx4 v132, s[34:35]
	s_mov_b32 m0, s42
	s_nop 0
	global_load_lds_dwordx4 v136, s[34:35]
	s_waitcnt vmcnt(8)
	s_waitcnt lgkmcnt(0)
	s_barrier
	s_waitcnt lgkmcnt(0)
	v_mfma_f32_16x16x32_bf16 v[62:65], v[152:155], v[194:197], v[62:65]
	v_mfma_f32_16x16x32_bf16 v[58:61], v[170:173], v[194:197], v[58:61]
	v_mfma_f32_16x16x32_bf16 v[46:49], v[152:155], v[208:211], v[46:49]
	v_mfma_f32_16x16x32_bf16 v[42:45], v[170:173], v[208:211], v[42:45]
	v_mfma_f32_16x16x32_bf16 v[30:33], v[152:155], v[216:219], v[30:33]
	v_mfma_f32_16x16x32_bf16 v[26:29], v[170:173], v[216:219], v[26:29]
	v_mfma_f32_16x16x32_bf16 v[14:17], v[152:155], v[224:227], v[14:17]
	v_mfma_f32_16x16x32_bf16 v[10:13], v[170:173], v[224:227], v[10:13]
	v_mfma_f32_16x16x32_bf16 v[62:65], v[156:159], v[204:207], v[62:65]
	v_mfma_f32_16x16x32_bf16 v[58:61], v[174:177], v[204:207], v[58:61]
	v_mfma_f32_16x16x32_bf16 v[46:49], v[156:159], v[212:215], v[46:49]
	v_mfma_f32_16x16x32_bf16 v[42:45], v[174:177], v[212:215], v[42:45]
	v_mfma_f32_16x16x32_bf16 v[30:33], v[156:159], v[220:223], v[30:33]
	v_mfma_f32_16x16x32_bf16 v[26:29], v[174:177], v[220:223], v[26:29]
	v_mfma_f32_16x16x32_bf16 v[14:17], v[156:159], v[228:231], v[14:17]
	v_mfma_f32_16x16x32_bf16 v[10:13], v[174:177], v[228:231], v[10:13]
	v_mfma_f32_16x16x32_bf16 v[54:57], v[178:181], v[194:197], v[54:57]
	v_mfma_f32_16x16x32_bf16 v[50:53], v[186:189], v[194:197], v[50:53]
	v_mfma_f32_16x16x32_bf16 v[38:41], v[178:181], v[208:211], v[38:41]
	v_mfma_f32_16x16x32_bf16 v[34:37], v[186:189], v[208:211], v[34:37]
	v_mfma_f32_16x16x32_bf16 v[22:25], v[178:181], v[216:219], v[22:25]
	v_mfma_f32_16x16x32_bf16 v[18:21], v[186:189], v[216:219], v[18:21]
	v_mfma_f32_16x16x32_bf16 v[6:9], v[178:181], v[224:227], v[6:9]
	v_mfma_f32_16x16x32_bf16 v[2:5], v[186:189], v[224:227], v[2:5]
	v_mfma_f32_16x16x32_bf16 v[54:57], v[182:185], v[204:207], v[54:57]
	v_mfma_f32_16x16x32_bf16 v[50:53], v[190:193], v[204:207], v[50:53]
	v_mfma_f32_16x16x32_bf16 v[38:41], v[182:185], v[212:215], v[38:41]
	v_mfma_f32_16x16x32_bf16 v[34:37], v[190:193], v[212:215], v[34:37]
	v_mfma_f32_16x16x32_bf16 v[22:25], v[182:185], v[220:223], v[22:25]
	v_mfma_f32_16x16x32_bf16 v[18:21], v[190:193], v[220:223], v[18:21]
	v_mfma_f32_16x16x32_bf16 v[6:9], v[182:185], v[228:231], v[6:9]
	v_mfma_f32_16x16x32_bf16 v[2:5], v[190:193], v[228:231], v[2:5]
	s_barrier
; #define PG8_STAGE(bufoff, gbase, voff) do { _Pragma("unroll") for (int _i = 0; _i < 2; ++_i) \
;         __builtin_amdgcn_global_load_lds((const unsigned*)((const char*)(gbase) + (voff)[_i]), (PG8_LAS unsigned*)(lds + (bufoff) + ldsw + _i * 8192), 16, 0, 0); } while (0)
; #define PG8_LDA(dst, b, h) do { _Pragma("unroll") for (int m = 0; m < 4; ++m) _Pragma("unroll") for (int k = 0; k < 2; ++k) dst[m][k] = *(const PG8_LAS bf16x8*)(lds + PG8_SA(b, h) + aoff + m * 2048 + k * 1024); } while (0)
; #define PG8_LDB(dst, b, h) do { _Pragma("unroll") for (int n = 0; n < 2; ++n) _Pragma("unroll") for (int k = 0; k < 2; ++k) dst[n][k] = *(const PG8_LAS bf16x8*)(lds + PG8_SB(b, h) + boff + n * 2048 + k * 1024); } while (0)
; #define PG8_MMA(ai, bj, At, Bt) do { __builtin_amdgcn_s_setprio(1); _Pragma("unroll") for (int m = 0; m < 4; ++m) _Pragma("unroll") for (int n = 0; n < 2; ++n) _Pragma("unroll") for (int k = 0; k < 2; ++k) \
;         acc[ai][bj][m][n] = __builtin_amdgcn_mfma_f32_16x16x32_bf16(Bt[n][k], At[m][k], acc[ai][bj][m][n], 0, 0, 0); __builtin_amdgcn_s_setprio(0); } while (0)
; #define PG8_WAIT_V(n) asm volatile("s_waitcnt vmcnt(" #n ")" ::: "memory")
; #define PG8_WAIT_L(n) asm volatile("s_waitcnt lgkmcnt(" #n ")" ::: "memory")
; #define PG8_BAR __builtin_amdgcn_s_barrier()
; #define PG8_SCHED __builtin_amdgcn_sched_barrier(0)
; template <class Epi, class Sched, bool ALIGN_EPI = false, bool SP2 = false>
; __device__ __forceinline__ void gemm_phase(PG8_LAS unsigned char* lds, const Gemm g, const Sched& S, const Epi& E) {
;     ...
;         for (int t = 0; t < nt; t += 2) {
;     ...
;             PG8_LDB(B0, 1, 0); PG8_LDB(B1, 1, 1); PG8_SCHED; PG8_LDA(At, 1, 0); PG8_STAGE(PG8_SA(0, 1), a2 + hstep, voffA);
;             PG8_WAIT_V(8); PG8_WAIT_L(0); PG8_BAR; PG8_MMA(0, 0, At, B0); PG8_MMA(0, 1, At, B1); PG8_BAR; PG8_SCHED;
;             PG8_LDA(At, 1, 1); PG8_STAGE(PG8_SB(1, 0), b3, voffB); PG8_STAGE(PG8_SB(1, 1), b3 + hstep, voffB); PG8_STAGE(PG8_SA(1, 0), a3, voffA);
;             PG8_WAIT_V(8); PG8_WAIT_L(0); PG8_BAR; PG8_MMA(1, 0, At, B0); PG8_MMA(1, 1, At, B1); PG8_BAR; PG8_SCHED;
	s_add_i32 s64, 0, 0x18000
	v_add_u32_e32 v140, s64, v160
	s_add_i32 s65, 0, 0x1c000
	ds_read_b128 v[152:155], v140
	ds_read_b128 v[156:159], v140 offset:1024
	ds_read_b128 v[170:173], v140 offset:2048
	ds_read_b128 v[174:177], v140 offset:3072
	v_add_u32_e32 v140, s65, v160
	ds_read_b128 v[178:181], v140
	ds_read_b128 v[182:185], v140 offset:1024
	ds_read_b128 v[186:189], v140 offset:2048
	ds_read_b128 v[190:193], v140 offset:3072
	s_add_u32 s34, s34, 0x80000
	s_addc_u32 s35, s35, 0
	s_mov_b32 m0, s43
	ds_read_b128 v[194:197], v166 offset:32768
	ds_read_b128 v[204:207], v166 offset:33792
	ds_read_b128 v[208:211], v166 offset:34816
	ds_read_b128 v[212:215], v166 offset:35840
	ds_read_b128 v[216:219], v166 offset:36864
	ds_read_b128 v[220:223], v166 offset:37888
	ds_read_b128 v[224:227], v166 offset:38912
	ds_read_b128 v[228:231], v166 offset:39936
	global_load_lds_dwordx4 v132, s[34:35]
	s_mov_b32 m0, s44
	s_nop 0
	global_load_lds_dwordx4 v136, s[34:35]
	s_waitcnt vmcnt(8)
	s_waitcnt lgkmcnt(0)
	s_barrier
	s_waitcnt lgkmcnt(0)
	v_mfma_f32_16x16x32_bf16 v[126:129], v[152:155], v[194:197], v[126:129]
	v_mfma_f32_16x16x32_bf16 v[122:125], v[170:173], v[194:197], v[122:125]
	v_mfma_f32_16x16x32_bf16 v[110:113], v[152:155], v[208:211], v[110:113]
	v_mfma_f32_16x16x32_bf16 v[106:109], v[170:173], v[208:211], v[106:109]
	v_mfma_f32_16x16x32_bf16 v[94:97], v[152:155], v[216:219], v[94:97]
	v_mfma_f32_16x16x32_bf16 v[90:93], v[170:173], v[216:219], v[90:93]
	v_mfma_f32_16x16x32_bf16 v[78:81], v[152:155], v[224:227], v[78:81]
	v_mfma_f32_16x16x32_bf16 v[74:77], v[170:173], v[224:227], v[74:77]
	v_mfma_f32_16x16x32_bf16 v[126:129], v[156:159], v[204:207], v[126:129]
	v_mfma_f32_16x16x32_bf16 v[122:125], v[174:177], v[204:207], v[122:125]
	v_mfma_f32_16x16x32_bf16 v[110:113], v[156:159], v[212:215], v[110:113]
	v_mfma_f32_16x16x32_bf16 v[106:109], v[174:177], v[212:215], v[106:109]
	v_mfma_f32_16x16x32_bf16 v[94:97], v[156:159], v[220:223], v[94:97]
	v_mfma_f32_16x16x32_bf16 v[90:93], v[174:177], v[220:223], v[90:93]
	v_mfma_f32_16x16x32_bf16 v[78:81], v[156:159], v[228:231], v[78:81]
	v_mfma_f32_16x16x32_bf16 v[74:77], v[174:177], v[228:231], v[74:77]
	v_mfma_f32_16x16x32_bf16 v[118:121], v[178:181], v[194:197], v[118:121]
	v_mfma_f32_16x16x32_bf16 v[114:117], v[186:189], v[194:197], v[114:117]
	v_mfma_f32_16x16x32_bf16 v[102:105], v[178:181], v[208:211], v[102:105]
	v_mfma_f32_16x16x32_bf16 v[98:101], v[186:189], v[208:211], v[98:101]
	v_mfma_f32_16x16x32_bf16 v[86:89], v[178:181], v[216:219], v[86:89]
	v_mfma_f32_16x16x32_bf16 v[82:85], v[186:189], v[216:219], v[82:85]
	v_mfma_f32_16x16x32_bf16 v[70:73], v[178:181], v[224:227], v[70:73]
	v_mfma_f32_16x16x32_bf16 v[66:69], v[186:189], v[224:227], v[66:69]
	v_mfma_f32_16x16x32_bf16 v[118:121], v[182:185], v[204:207], v[118:121]
	v_mfma_f32_16x16x32_bf16 v[114:117], v[190:193], v[204:207], v[114:117]
	v_mfma_f32_16x16x32_bf16 v[102:105], v[182:185], v[212:215], v[102:105]
	v_mfma_f32_16x16x32_bf16 v[98:101], v[190:193], v[212:215], v[98:101]
	v_mfma_f32_16x16x32_bf16 v[86:89], v[182:185], v[220:223], v[86:89]
	v_mfma_f32_16x16x32_bf16 v[82:85], v[190:193], v[220:223], v[82:85]
	v_mfma_f32_16x16x32_bf16 v[70:73], v[182:185], v[228:231], v[70:73]
	v_mfma_f32_16x16x32_bf16 v[66:69], v[190:193], v[228:231], v[66:69]
	s_barrier
	s_add_i32 s34, s64, s36
	s_mov_b32 m0, s34
	ds_read_b128 v[194:197], v166 offset:49152
	ds_read_b128 v[204:207], v166 offset:50176
	ds_read_b128 v[208:211], v166 offset:51200
	ds_read_b128 v[212:215], v166 offset:52224
	ds_read_b128 v[216:219], v166 offset:53248
	ds_read_b128 v[220:223], v166 offset:54272
	ds_read_b128 v[224:227], v166 offset:55296
	ds_read_b128 v[228:231], v166 offset:56320
	global_load_lds_dwordx4 v134, s[66:67]
	s_add_i32 m0, s34, 0x2000
	s_add_u32 s30, s30, 0x80080
	s_addc_u32 s31, s31, 0
	s_add_i32 s34, s65, s36
	global_load_lds_dwordx4 v138, s[66:67]
	s_mov_b32 m0, s34
	s_nop 0
	global_load_lds_dwordx4 v134, s[30:31]
	s_add_i32 m0, s34, 0x2000
	s_nop 0
	global_load_lds_dwordx4 v138, s[30:31]
	s_mov_b32 m0, s79
	s_nop 0
	global_load_lds_dwordx4 v132, s[68:69]
	s_mov_b32 m0, s80
	s_nop 0
	global_load_lds_dwordx4 v136, s[68:69]
	s_waitcnt vmcnt(8)
	s_waitcnt lgkmcnt(0)
	s_barrier
	s_waitcnt lgkmcnt(0)
	v_mfma_f32_16x16x32_bf16 v[62:65], v[152:155], v[194:197], v[62:65]
	v_mfma_f32_16x16x32_bf16 v[58:61], v[170:173], v[194:197], v[58:61]
	v_mfma_f32_16x16x32_bf16 v[46:49], v[152:155], v[208:211], v[46:49]
	v_mfma_f32_16x16x32_bf16 v[42:45], v[170:173], v[208:211], v[42:45]
	v_mfma_f32_16x16x32_bf16 v[30:33], v[152:155], v[216:219], v[30:33]
	v_mfma_f32_16x16x32_bf16 v[26:29], v[170:173], v[216:219], v[26:29]
	v_mfma_f32_16x16x32_bf16 v[14:17], v[152:155], v[224:227], v[14:17]
	v_mfma_f32_16x16x32_bf16 v[10:13], v[170:173], v[224:227], v[10:13]
	v_mfma_f32_16x16x32_bf16 v[62:65], v[156:159], v[204:207], v[62:65]
	v_mfma_f32_16x16x32_bf16 v[58:61], v[174:177], v[204:207], v[58:61]
	v_mfma_f32_16x16x32_bf16 v[46:49], v[156:159], v[212:215], v[46:49]
	v_mfma_f32_16x16x32_bf16 v[42:45], v[174:177], v[212:215], v[42:45]
	v_mfma_f32_16x16x32_bf16 v[30:33], v[156:159], v[220:223], v[30:33]
	v_mfma_f32_16x16x32_bf16 v[26:29], v[174:177], v[220:223], v[26:29]
	v_mfma_f32_16x16x32_bf16 v[14:17], v[156:159], v[228:231], v[14:17]
	v_mfma_f32_16x16x32_bf16 v[10:13], v[174:177], v[228:231], v[10:13]
	v_mfma_f32_16x16x32_bf16 v[54:57], v[178:181], v[194:197], v[54:57]
	v_mfma_f32_16x16x32_bf16 v[50:53], v[186:189], v[194:197], v[50:53]
	v_mfma_f32_16x16x32_bf16 v[38:41], v[178:181], v[208:211], v[38:41]
	v_mfma_f32_16x16x32_bf16 v[34:37], v[186:189], v[208:211], v[34:37]
	v_mfma_f32_16x16x32_bf16 v[22:25], v[178:181], v[216:219], v[22:25]
	v_mfma_f32_16x16x32_bf16 v[18:21], v[186:189], v[216:219], v[18:21]
	v_mfma_f32_16x16x32_bf16 v[6:9], v[178:181], v[224:227], v[6:9]
	v_mfma_f32_16x16x32_bf16 v[2:5], v[186:189], v[224:227], v[2:5]
	v_mfma_f32_16x16x32_bf16 v[54:57], v[182:185], v[204:207], v[54:57]
	v_mfma_f32_16x16x32_bf16 v[50:53], v[190:193], v[204:207], v[50:53]
	v_mfma_f32_16x16x32_bf16 v[38:41], v[182:185], v[212:215], v[38:41]
	v_mfma_f32_16x16x32_bf16 v[34:37], v[190:193], v[212:215], v[34:37]
	v_mfma_f32_16x16x32_bf16 v[22:25], v[182:185], v[220:223], v[22:25]
	v_mfma_f32_16x16x32_bf16 v[18:21], v[190:193], v[220:223], v[18:21]
	v_mfma_f32_16x16x32_bf16 v[6:9], v[182:185], v[228:231], v[6:9]
	v_mfma_f32_16x16x32_bf16 v[2:5], v[190:193], v[228:231], v[2:5]
	s_barrier
	s_add_i32 s85, s85, 2
	s_add_u32 s28, s28, 0x100
	s_addc_u32 s29, s29, 0
	s_add_u32 s71, s71, 0x100
	s_addc_u32 s84, s84, 0
	s_cmp_gt_u32 s85, 29
	s_cbranch_scc0 .LBB0_765
	s_and_b64 vcc, exec, s[18:19]
	s_cbranch_vccz .LBB0_768
	s_barrier

; #define PG8_STAGE(bufoff, gbase, voff) do { _Pragma("unroll") for (int _i = 0; _i < 2; ++_i) \
;         __builtin_amdgcn_global_load_lds((const unsigned*)((const char*)(gbase) + (voff)[_i]), (PG8_LAS unsigned*)(lds + (bufoff) + ldsw + _i * 8192), 16, 0, 0); } while (0)
; #define PG8_WAIT_V(n) asm volatile("s_waitcnt vmcnt(" #n ")" ::: "memory")
; #define PG8_BAR __builtin_amdgcn_s_barrier()
; template <class Epi, class Sched, bool ALIGN_EPI = false, bool SP2 = false>
; __device__ __forceinline__ void gemm_phase(PG8_LAS unsigned char* lds, const Gemm g, const Sched& S, const Epi& E) {
;     const int tid = threadIdx.x, wid = __builtin_amdgcn_readfirstlane(tid >> 6), lane = tid & 63, wr = wid >> 2, wc = wid & 3, fr = lane & 15, fq = lane >> 4;
;     const int K = g.K, nt = K / BK;
;     unsigned voffA[2], voffB[2];
; #pragma unroll
;     for (int i = 0; i < 2; ++i) { int R, C; stage_rc(tid * 16 + i * 8192, R, C); const int Rb = Epi::PERM ? ((R & ~31) + perm32(R & 31)) : R;
;         voffA[i] = (unsigned)(R * K + C) * 2u; voffB[i] = (unsigned)(Rb * K + C) * 2u; }
;     ...
;     const char* cA = (const char*)g.A + (size_t)cur.pm * tstep; const char* cB = (const char*)g.Bt + (size_t)cur.pn * tstep;
;     S.a_ready(cur);
;     if constexpr (SP2) {
;         PG8_STAGE(PG8_SB(0, 0), cB, voffB); PG8_STAGE(PG8_SB(0, 1), cB + hstep, voffB); PG8_STAGE(PG8_SA(0, 0), cA, voffA); PG8_STAGE(PG8_SA(0, 1), cA + hstep, voffA);
;         if (wr == 1) PG8_BAR;
;         PG8_WAIT_V(2); PG8_BAR;
;         PG8_STAGE(PG8_SB(1, 0), cB + kstep, voffB); PG8_STAGE(PG8_SA(1, 0), cA + kstep, voffA); PG8_STAGE(PG8_SB(1, 1), cB + hstep + kstep, voffB);
;         PG8_WAIT_V(6); PG8_BAR;
;     } else {
;         PG8_STAGE(PG8_SB(0, 0), cB, voffB); PG8_STAGE(PG8_SA(0, 0), cA, voffA); PG8_STAGE(PG8_SB(0, 1), cB + hstep, voffB); PG8_STAGE(PG8_SA(0, 1), cA + hstep, voffA);
;         if (wr == 1) PG8_BAR;
.LBB0_1167:
	s_cmp_lt_i32 s72, 12
	s_cselect_b64 s[0:1], -1, 0
	s_cmp_gt_i32 s73, 11
	s_cselect_b64 s[2:3], -1, 0
	s_and_b64 s[0:1], s[0:1], s[2:3]
	s_andn2_b64 vcc, exec, s[0:1]
	s_cbranch_vccnz .LBB0_1250
	v_and_b32_e32 v1, 0x3ff, v0
	s_cmpk_gt_i32 s33, 0x4ff
	v_readfirstlane_b32 s2, v1
	s_cbranch_scc1 .LBB0_1200
	v_lshrrev_b32_e32 v4, 1, v1
	v_lshrrev_b32_e32 v5, 5, v1
	v_and_b32_e32 v4, 24, v4
	v_and_b32_e32 v5, 4, v5
	v_bfe_u32 v6, v1, 2, 2
	s_add_u32 s30, s50, 0x3440000
	v_lshlrev_b32_e32 v2, 4, v1
	v_and_b32_e32 v3, 32, v1
	v_bfe_u32 v12, v1, 2, 4
	v_or3_b32 v4, v5, v6, v4
	v_lshrrev_b32_e32 v5, 3, v1
	s_movk_i32 s0, 0x70
	s_addc_u32 s31, s51, 0
	v_bitop3_b32 v10, v2, v3, 48 bitop3:0x6c
	v_and_b32_e32 v11, 64, v1
	v_and_or_b32 v6, v5, s0, v12
	s_movk_i32 s0, 0x60
	v_add_u32_e32 v13, 0x2000, v2
	s_add_u32 s34, s50, 0x1f940000
	v_or_b32_e32 v3, v10, v11
	v_and_or_b32 v5, v5, s0, v4
	v_lshrrev_b32_e32 v2, 7, v13
	s_movk_i32 s0, 0xf0
	s_addc_u32 s35, s51, 0
	v_lshl_or_b32 v132, v5, 12, v3
	v_and_or_b32 v5, v2, s0, v12
	s_movk_i32 s0, 0xe0
	s_ashr_i32 s36, s33, 31
	v_and_or_b32 v2, v2, s0, v4
	s_lshr_b32 s0, s36, 29
	s_add_i32 s0, s33, s0
	s_ashr_i32 s1, s0, 3
	s_and_b32 s0, s0, -8
	s_sub_i32 s0, s33, s0
	s_cmp_lt_i32 s0, 0
	s_movk_i32 s37, 0xa1
	s_cselect_b32 s3, s37, 0xa0
	s_mul_i32 s0, s3, s0
	s_add_i32 s0, s0, s1
	s_ashr_i32 s1, s0, 31
	s_lshr_b32 s1, s1, 27
	s_add_i32 s1, s0, s1
	s_ashr_i32 s3, s1, 5
	s_and_b32 s1, s1, 0xffe0
	s_sub_i32 s1, s0, s1
	s_bfe_i32 s0, s1, 0x80000
	s_bfe_u32 s0, s0, 0x2000d
	s_add_i32 s4, s1, s0
	s_bfe_i32 s0, s4, 0x80000
	s_and_b32 s4, s4, 0xfc
	s_sub_i32 s1, s1, s4
	s_lshl_b32 s3, s3, 2
	s_sext_i32_i16 s0, s0
	s_sext_i32_i8 s1, s1
	s_lshr_b32 s0, s0, 2
	s_add_i32 s4, s3, s1
	s_lshr_b32 s1, s2, 6
	s_ashr_i32 s5, s4, 31
	s_bfe_i64 s[8:9], s[0:1], 0x100000
	s_lshr_b32 s3, s2, 8
	s_lshl_b32 s38, s1, 10
	s_lshl_b64 s[6:7], s[4:5], 20
	s_lshl_b64 s[8:9], s[8:9], 20
	s_add_u32 s26, s30, s8
	s_addc_u32 s27, s31, s9
	s_add_i32 s39, s38, 0
	s_add_i32 m0, s39, 0x10000
	v_lshl_or_b32 v136, v2, 12, v3
	global_load_lds_dwordx4 v132, s[26:27]
	s_add_i32 m0, s39, 0x12000
	s_add_u32 s8, s26, 0x80000
	global_load_lds_dwordx4 v136, s[26:27]
	s_addc_u32 s9, s27, 0
	s_add_i32 m0, s39, 0x14000
	v_lshl_or_b32 v130, v6, 12, v3
	global_load_lds_dwordx4 v132, s[8:9]
	s_add_i32 m0, s39, 0x16000
	s_add_u32 s24, s34, s6
	s_addc_u32 s25, s35, s7
	s_add_i32 s40, s39, 0x2000
	global_load_lds_dwordx4 v136, s[8:9]
	s_mov_b32 m0, s39
	s_add_u32 s6, s24, 0x80000
	v_lshl_or_b32 v134, v5, 12, v3
	global_load_lds_dwordx4 v130, s[24:25]
	s_mov_b32 m0, s40
	s_addc_u32 s7, s25, 0
	s_add_i32 s41, s39, 0x4000
	global_load_lds_dwordx4 v134, s[24:25]
	s_mov_b32 m0, s41
	s_add_i32 s42, s39, 0x6000
	global_load_lds_dwordx4 v130, s[6:7]
	s_mov_b32 m0, s42
	v_mov_b32_e32 v133, 0
	global_load_lds_dwordx4 v134, s[6:7]
	v_mov_b32_e32 v137, v133
	v_mov_b32_e32 v131, v133
	v_mov_b32_e32 v135, v133
	s_cmp_eq_u32 s3, 1
	s_mov_b32 s5, 0
	v_lshl_add_u64 v[8:9], s[26:27], 0, v[132:133]
	s_waitcnt lgkmcnt(0)
	v_lshl_add_u64 v[6:7], s[26:27], 0, v[136:137]
	v_lshl_add_u64 v[2:3], s[24:25], 0, v[130:131]
	s_cselect_b64 s[6:7], -1, 0
	s_cmp_lg_u32 s3, 1
	v_lshl_add_u64 v[4:5], s[24:25], 0, v[134:135]
	s_cbranch_scc1 .LBB0_1171
	s_setprio 1
	s_barrier

; #define PG8_STAGE(bufoff, gbase, voff) do { _Pragma("unroll") for (int _i = 0; _i < 2; ++_i) \
;         __builtin_amdgcn_global_load_lds((const unsigned*)((const char*)(gbase) + (voff)[_i]), (PG8_LAS unsigned*)(lds + (bufoff) + ldsw + _i * 8192), 16, 0, 0); } while (0)
; #define PG8_LDA(dst, b, h) do { _Pragma("unroll") for (int m = 0; m < 4; ++m) _Pragma("unroll") for (int k = 0; k < 2; ++k) dst[m][k] = *(const PG8_LAS bf16x8*)(lds + PG8_SA(b, h) + aoff + m * 2048 + k * 1024); } while (0)
; #define PG8_LDB(dst, b, h) do { _Pragma("unroll") for (int n = 0; n < 2; ++n) _Pragma("unroll") for (int k = 0; k < 2; ++k) dst[n][k] = *(const PG8_LAS bf16x8*)(lds + PG8_SB(b, h) + boff + n * 2048 + k * 1024); } while (0)
; #define PG8_MMA(ai, bj, At, Bt) do { __builtin_amdgcn_s_setprio(1); _Pragma("unroll") for (int m = 0; m < 4; ++m) _Pragma("unroll") for (int n = 0; n < 2; ++n) _Pragma("unroll") for (int k = 0; k < 2; ++k) \
;         acc[ai][bj][m][n] = __builtin_amdgcn_mfma_f32_16x16x32_bf16(Bt[n][k], At[m][k], acc[ai][bj][m][n], 0, 0, 0); __builtin_amdgcn_s_setprio(0); } while (0)
; #define PG8_WAIT_V(n) asm volatile("s_waitcnt vmcnt(" #n ")" ::: "memory")
; #define PG8_WAIT_L(n) asm volatile("s_waitcnt lgkmcnt(" #n ")" ::: "memory")
; #define PG8_BAR __builtin_amdgcn_s_barrier()
; #define PG8_SCHED __builtin_amdgcn_sched_barrier(0)
; template <class Epi, class Sched, bool ALIGN_EPI = false, bool SP2 = false>
; __device__ __forceinline__ void gemm_phase(PG8_LAS unsigned char* lds, const Gemm g, const Sched& S, const Epi& E) {
;     ...
;             PG8_LDB(B0, 0, 0); PG8_LDB(B1, 0, 1); PG8_SCHED; PG8_LDA(At, 0, 0); PG8_STAGE(PG8_SA(1, 1), a1 + hstep, voffA);
;             PG8_WAIT_V(8); PG8_WAIT_L(0); PG8_BAR; PG8_MMA(0, 0, At, B0); PG8_MMA(0, 1, At, B1); PG8_BAR; PG8_SCHED;
;             PG8_LDA(At, 0, 1); PG8_STAGE(PG8_SB(0, 0), b2, voffB); PG8_STAGE(PG8_SB(0, 1), b2 + hstep, voffB); PG8_STAGE(PG8_SA(0, 0), a2, voffA);
;             PG8_WAIT_V(8); PG8_WAIT_L(0); PG8_BAR; PG8_MMA(1, 0, At, B0); PG8_MMA(1, 1, At, B1); PG8_BAR; PG8_SCHED;
.LBB0_1177:
	ds_read_b128 v[146:149], v153
	ds_read_b128 v[158:161], v153 offset:1024
	ds_read_b128 v[162:165], v153 offset:2048
	ds_read_b128 v[166:169], v153 offset:3072
	ds_read_b128 v[170:173], v154
	ds_read_b128 v[174:177], v154 offset:1024
	ds_read_b128 v[178:181], v154 offset:2048
	ds_read_b128 v[182:185], v154 offset:3072
	s_add_u32 s26, s24, 0xfff80080
	s_addc_u32 s27, s25, -1
	s_cmp_eq_u32 s65, 28
	s_cselect_b32 s29, s19, s27
	s_cselect_b32 s28, s57, s26
	s_cselect_b32 s27, s17, s64
	s_cselect_b32 s26, s58, s59
	s_add_i32 m0, s39, 0xc000
	ds_read_b128 v[186:189], v155
	ds_read_b128 v[190:193], v155 offset:1024
	ds_read_b128 v[194:197], v155 offset:2048
	ds_read_b128 v[202:205], v155 offset:3072
	ds_read_b128 v[206:209], v155 offset:4096
	ds_read_b128 v[210:213], v155 offset:5120
	ds_read_b128 v[214:217], v155 offset:6144
	ds_read_b128 v[218:221], v155 offset:7168
	global_load_lds_dwordx4 v138, s[24:25]
	s_add_i32 m0, s39, 0xe000
	s_nop 0
	global_load_lds_dwordx4 v140, s[24:25]
	s_waitcnt vmcnt(8)
	s_waitcnt lgkmcnt(0)
	s_barrier
	s_waitcnt lgkmcnt(0)
	v_mfma_f32_16x16x32_bf16 v[126:129], v[146:149], v[186:189], v[126:129]
	v_mfma_f32_16x16x32_bf16 v[122:125], v[162:165], v[186:189], v[122:125]
	v_mfma_f32_16x16x32_bf16 v[110:113], v[146:149], v[194:197], v[110:113]
	v_mfma_f32_16x16x32_bf16 v[106:109], v[162:165], v[194:197], v[106:109]
	v_mfma_f32_16x16x32_bf16 v[94:97], v[146:149], v[206:209], v[94:97]
	v_mfma_f32_16x16x32_bf16 v[90:93], v[162:165], v[206:209], v[90:93]
	v_mfma_f32_16x16x32_bf16 v[78:81], v[146:149], v[214:217], v[78:81]
	v_mfma_f32_16x16x32_bf16 v[74:77], v[162:165], v[214:217], v[74:77]
	v_mfma_f32_16x16x32_bf16 v[126:129], v[158:161], v[190:193], v[126:129]
	v_mfma_f32_16x16x32_bf16 v[122:125], v[166:169], v[190:193], v[122:125]
	v_mfma_f32_16x16x32_bf16 v[110:113], v[158:161], v[202:205], v[110:113]
	v_mfma_f32_16x16x32_bf16 v[106:109], v[166:169], v[202:205], v[106:109]
	v_mfma_f32_16x16x32_bf16 v[94:97], v[158:161], v[210:213], v[94:97]
	v_mfma_f32_16x16x32_bf16 v[90:93], v[166:169], v[210:213], v[90:93]
	v_mfma_f32_16x16x32_bf16 v[78:81], v[158:161], v[218:221], v[78:81]
	v_mfma_f32_16x16x32_bf16 v[74:77], v[166:169], v[218:221], v[74:77]
	v_mfma_f32_16x16x32_bf16 v[118:121], v[170:173], v[186:189], v[118:121]
	v_mfma_f32_16x16x32_bf16 v[114:117], v[178:181], v[186:189], v[114:117]
	v_mfma_f32_16x16x32_bf16 v[102:105], v[170:173], v[194:197], v[102:105]
	v_mfma_f32_16x16x32_bf16 v[98:101], v[178:181], v[194:197], v[98:101]
	v_mfma_f32_16x16x32_bf16 v[86:89], v[170:173], v[206:209], v[86:89]
	v_mfma_f32_16x16x32_bf16 v[82:85], v[178:181], v[206:209], v[82:85]
	v_mfma_f32_16x16x32_bf16 v[70:73], v[170:173], v[214:217], v[70:73]
	v_mfma_f32_16x16x32_bf16 v[66:69], v[178:181], v[214:217], v[66:69]
	v_mfma_f32_16x16x32_bf16 v[118:121], v[174:177], v[190:193], v[118:121]
	v_mfma_f32_16x16x32_bf16 v[114:117], v[182:185], v[190:193], v[114:117]
	v_mfma_f32_16x16x32_bf16 v[102:105], v[174:177], v[202:205], v[102:105]
	v_mfma_f32_16x16x32_bf16 v[98:101], v[182:185], v[202:205], v[98:101]
	v_mfma_f32_16x16x32_bf16 v[86:89], v[174:177], v[210:213], v[86:89]
	v_mfma_f32_16x16x32_bf16 v[82:85], v[182:185], v[210:213], v[82:85]
	v_mfma_f32_16x16x32_bf16 v[70:73], v[174:177], v[218:221], v[70:73]
	v_mfma_f32_16x16x32_bf16 v[66:69], v[182:185], v[218:221], v[66:69]
	s_barrier
	s_add_i32 s66, s53, s38
	s_add_u32 s70, s26, 0x80
	s_addc_u32 s71, s27, 0
	s_mov_b32 m0, s66
	ds_read_b128 v[186:189], v155 offset:16384
	ds_read_b128 v[190:193], v155 offset:17408
	ds_read_b128 v[194:197], v155 offset:18432
	ds_read_b128 v[202:205], v155 offset:19456
	ds_read_b128 v[206:209], v155 offset:20480
	ds_read_b128 v[210:213], v155 offset:21504
	ds_read_b128 v[214:217], v155 offset:22528
	ds_read_b128 v[218:221], v155 offset:23552
	global_load_lds_dwordx4 v132, s[26:27]
	s_add_i32 m0, s66, 0x2000
	s_add_u32 s66, s26, 0x80000
	s_addc_u32 s67, s27, 0
	s_add_i32 s68, s54, s38
	global_load_lds_dwordx4 v136, s[26:27]
	s_mov_b32 m0, s68
	s_add_u32 s74, s28, 0x80
	s_addc_u32 s75, s29, 0
	global_load_lds_dwordx4 v132, s[66:67]
	s_add_i32 m0, s68, 0x2000
	s_nop 0
	global_load_lds_dwordx4 v136, s[66:67]
	s_mov_b32 m0, s39
	s_nop 0
	global_load_lds_dwordx4 v130, s[28:29]
	s_mov_b32 m0, s40
	s_nop 0
	global_load_lds_dwordx4 v134, s[28:29]
	s_waitcnt vmcnt(8)
	s_waitcnt lgkmcnt(0)
	s_barrier
	s_waitcnt lgkmcnt(0)
	v_mfma_f32_16x16x32_bf16 v[62:65], v[146:149], v[186:189], v[62:65]
	v_mfma_f32_16x16x32_bf16 v[58:61], v[162:165], v[186:189], v[58:61]
	v_mfma_f32_16x16x32_bf16 v[46:49], v[146:149], v[194:197], v[46:49]
	v_mfma_f32_16x16x32_bf16 v[42:45], v[162:165], v[194:197], v[42:45]
	v_mfma_f32_16x16x32_bf16 v[30:33], v[146:149], v[206:209], v[30:33]
	v_mfma_f32_16x16x32_bf16 v[26:29], v[162:165], v[206:209], v[26:29]
	v_mfma_f32_16x16x32_bf16 v[14:17], v[146:149], v[214:217], v[14:17]
	v_mfma_f32_16x16x32_bf16 v[10:13], v[162:165], v[214:217], v[10:13]
	v_mfma_f32_16x16x32_bf16 v[62:65], v[158:161], v[190:193], v[62:65]
	v_mfma_f32_16x16x32_bf16 v[58:61], v[166:169], v[190:193], v[58:61]
	v_mfma_f32_16x16x32_bf16 v[46:49], v[158:161], v[202:205], v[46:49]
	v_mfma_f32_16x16x32_bf16 v[42:45], v[166:169], v[202:205], v[42:45]
	v_mfma_f32_16x16x32_bf16 v[30:33], v[158:161], v[210:213], v[30:33]
	v_mfma_f32_16x16x32_bf16 v[26:29], v[166:169], v[210:213], v[26:29]
	v_mfma_f32_16x16x32_bf16 v[14:17], v[158:161], v[218:221], v[14:17]
	v_mfma_f32_16x16x32_bf16 v[10:13], v[166:169], v[218:221], v[10:13]
	v_mfma_f32_16x16x32_bf16 v[54:57], v[170:173], v[186:189], v[54:57]
	v_mfma_f32_16x16x32_bf16 v[50:53], v[178:181], v[186:189], v[50:53]
	v_mfma_f32_16x16x32_bf16 v[38:41], v[170:173], v[194:197], v[38:41]
	v_mfma_f32_16x16x32_bf16 v[34:37], v[178:181], v[194:197], v[34:37]
	v_mfma_f32_16x16x32_bf16 v[22:25], v[170:173], v[206:209], v[22:25]
	v_mfma_f32_16x16x32_bf16 v[18:21], v[178:181], v[206:209], v[18:21]
	v_mfma_f32_16x16x32_bf16 v[6:9], v[170:173], v[214:217], v[6:9]
	v_mfma_f32_16x16x32_bf16 v[2:5], v[178:181], v[214:217], v[2:5]
	v_mfma_f32_16x16x32_bf16 v[54:57], v[174:177], v[190:193], v[54:57]
	v_mfma_f32_16x16x32_bf16 v[50:53], v[182:185], v[190:193], v[50:53]
	v_mfma_f32_16x16x32_bf16 v[38:41], v[174:177], v[202:205], v[38:41]
	v_mfma_f32_16x16x32_bf16 v[34:37], v[182:185], v[202:205], v[34:37]
	v_mfma_f32_16x16x32_bf16 v[22:25], v[174:177], v[210:213], v[22:25]
	v_mfma_f32_16x16x32_bf16 v[18:21], v[182:185], v[210:213], v[18:21]
	v_mfma_f32_16x16x32_bf16 v[6:9], v[174:177], v[218:221], v[6:9]
	v_mfma_f32_16x16x32_bf16 v[2:5], v[182:185], v[218:221], v[2:5]
	s_barrier
; #define PG8_STAGE(bufoff, gbase, voff) do { _Pragma("unroll") for (int _i = 0; _i < 2; ++_i) \
;         __builtin_amdgcn_global_load_lds((const unsigned*)((const char*)(gbase) + (voff)[_i]), (PG8_LAS unsigned*)(lds + (bufoff) + ldsw + _i * 8192), 16, 0, 0); } while (0)
; #define PG8_LDA(dst, b, h) do { _Pragma("unroll") for (int m = 0; m < 4; ++m) _Pragma("unroll") for (int k = 0; k < 2; ++k) dst[m][k] = *(const PG8_LAS bf16x8*)(lds + PG8_SA(b, h) + aoff + m * 2048 + k * 1024); } while (0)
; #define PG8_LDB(dst, b, h) do { _Pragma("unroll") for (int n = 0; n < 2; ++n) _Pragma("unroll") for (int k = 0; k < 2; ++k) dst[n][k] = *(const PG8_LAS bf16x8*)(lds + PG8_SB(b, h) + boff + n * 2048 + k * 1024); } while (0)
; #define PG8_MMA(ai, bj, At, Bt) do { __builtin_amdgcn_s_setprio(1); _Pragma("unroll") for (int m = 0; m < 4; ++m) _Pragma("unroll") for (int n = 0; n < 2; ++n) _Pragma("unroll") for (int k = 0; k < 2; ++k) \
;         acc[ai][bj][m][n] = __builtin_amdgcn_mfma_f32_16x16x32_bf16(Bt[n][k], At[m][k], acc[ai][bj][m][n], 0, 0, 0); __builtin_amdgcn_s_setprio(0); } while (0)
; #define PG8_WAIT_V(n) asm volatile("s_waitcnt vmcnt(" #n ")" ::: "memory")
; #define PG8_WAIT_L(n) asm volatile("s_waitcnt lgkmcnt(" #n ")" ::: "memory")
; #define PG8_BAR __builtin_amdgcn_s_barrier()
; #define PG8_SCHED __builtin_amdgcn_sched_barrier(0)
; template <class Epi, class Sched, bool ALIGN_EPI = false, bool SP2 = false>
; __device__ __forceinline__ void gemm_phase(PG8_LAS unsigned char* lds, const Gemm g, const Sched& S, const Epi& E) {
;     ...
;         for (int t = 0; t < nt; t += 2) {
;     ...
;             PG8_LDB(B0, 1, 0); PG8_LDB(B1, 1, 1); PG8_SCHED; PG8_LDA(At, 1, 0); PG8_STAGE(PG8_SA(0, 1), a2 + hstep, voffA);
;             PG8_WAIT_V(8); PG8_WAIT_L(0); PG8_BAR; PG8_MMA(0, 0, At, B0); PG8_MMA(0, 1, At, B1); PG8_BAR; PG8_SCHED;
;             PG8_LDA(At, 1, 1); PG8_STAGE(PG8_SB(1, 0), b3, voffB); PG8_STAGE(PG8_SB(1, 1), b3 + hstep, voffB); PG8_STAGE(PG8_SA(1, 0), a3, voffA);
;             PG8_WAIT_V(8); PG8_WAIT_L(0); PG8_BAR; PG8_MMA(1, 0, At, B0); PG8_MMA(1, 1, At, B1); PG8_BAR; PG8_SCHED;
	s_add_i32 s66, 0, 0x18000
	v_add_u32_e32 v157, s66, v151
	s_add_i32 s67, 0, 0x1c000
	ds_read_b128 v[146:149], v157
	ds_read_b128 v[158:161], v157 offset:1024
	ds_read_b128 v[162:165], v157 offset:2048
	ds_read_b128 v[166:169], v157 offset:3072
	v_add_u32_e32 v157, s67, v151
	ds_read_b128 v[170:173], v157
	ds_read_b128 v[174:177], v157 offset:1024
	ds_read_b128 v[178:181], v157 offset:2048
	ds_read_b128 v[182:185], v157 offset:3072
	s_add_u32 s28, s28, 0x80000
	s_addc_u32 s29, s29, 0
	s_mov_b32 m0, s41
	ds_read_b128 v[186:189], v155 offset:32768
	ds_read_b128 v[190:193], v155 offset:33792
	ds_read_b128 v[194:197], v155 offset:34816
	ds_read_b128 v[202:205], v155 offset:35840
	ds_read_b128 v[206:209], v155 offset:36864
	ds_read_b128 v[210:213], v155 offset:37888
	ds_read_b128 v[214:217], v155 offset:38912
	ds_read_b128 v[218:221], v155 offset:39936
	global_load_lds_dwordx4 v130, s[28:29]
	s_mov_b32 m0, s42
	s_nop 0
	global_load_lds_dwordx4 v134, s[28:29]
	s_waitcnt vmcnt(8)
	s_waitcnt lgkmcnt(0)
	s_barrier
	s_waitcnt lgkmcnt(0)
	v_mfma_f32_16x16x32_bf16 v[126:129], v[146:149], v[186:189], v[126:129]
	v_mfma_f32_16x16x32_bf16 v[122:125], v[162:165], v[186:189], v[122:125]
	v_mfma_f32_16x16x32_bf16 v[110:113], v[146:149], v[194:197], v[110:113]
	v_mfma_f32_16x16x32_bf16 v[106:109], v[162:165], v[194:197], v[106:109]
	v_mfma_f32_16x16x32_bf16 v[94:97], v[146:149], v[206:209], v[94:97]
	v_mfma_f32_16x16x32_bf16 v[90:93], v[162:165], v[206:209], v[90:93]
	v_mfma_f32_16x16x32_bf16 v[78:81], v[146:149], v[214:217], v[78:81]
	v_mfma_f32_16x16x32_bf16 v[74:77], v[162:165], v[214:217], v[74:77]
	v_mfma_f32_16x16x32_bf16 v[126:129], v[158:161], v[190:193], v[126:129]
	v_mfma_f32_16x16x32_bf16 v[122:125], v[166:169], v[190:193], v[122:125]
	v_mfma_f32_16x16x32_bf16 v[110:113], v[158:161], v[202:205], v[110:113]
	v_mfma_f32_16x16x32_bf16 v[106:109], v[166:169], v[202:205], v[106:109]
	v_mfma_f32_16x16x32_bf16 v[94:97], v[158:161], v[210:213], v[94:97]
	v_mfma_f32_16x16x32_bf16 v[90:93], v[166:169], v[210:213], v[90:93]
	v_mfma_f32_16x16x32_bf16 v[78:81], v[158:161], v[218:221], v[78:81]
	v_mfma_f32_16x16x32_bf16 v[74:77], v[166:169], v[218:221], v[74:77]
	v_mfma_f32_16x16x32_bf16 v[118:121], v[170:173], v[186:189], v[118:121]
	v_mfma_f32_16x16x32_bf16 v[114:117], v[178:181], v[186:189], v[114:117]
	v_mfma_f32_16x16x32_bf16 v[102:105], v[170:173], v[194:197], v[102:105]
	v_mfma_f32_16x16x32_bf16 v[98:101], v[178:181], v[194:197], v[98:101]
	v_mfma_f32_16x16x32_bf16 v[86:89], v[170:173], v[206:209], v[86:89]
	v_mfma_f32_16x16x32_bf16 v[82:85], v[178:181], v[206:209], v[82:85]
	v_mfma_f32_16x16x32_bf16 v[70:73], v[170:173], v[214:217], v[70:73]
	v_mfma_f32_16x16x32_bf16 v[66:69], v[178:181], v[214:217], v[66:69]
	v_mfma_f32_16x16x32_bf16 v[118:121], v[174:177], v[190:193], v[118:121]
	v_mfma_f32_16x16x32_bf16 v[114:117], v[182:185], v[190:193], v[114:117]
	v_mfma_f32_16x16x32_bf16 v[102:105], v[174:177], v[202:205], v[102:105]
	v_mfma_f32_16x16x32_bf16 v[98:101], v[182:185], v[202:205], v[98:101]
	v_mfma_f32_16x16x32_bf16 v[86:89], v[174:177], v[210:213], v[86:89]
	v_mfma_f32_16x16x32_bf16 v[82:85], v[182:185], v[210:213], v[82:85]
	v_mfma_f32_16x16x32_bf16 v[70:73], v[174:177], v[218:221], v[70:73]
	v_mfma_f32_16x16x32_bf16 v[66:69], v[182:185], v[218:221], v[66:69]
	s_barrier
	s_add_i32 s28, s66, s38
	s_mov_b32 m0, s28
	ds_read_b128 v[186:189], v155 offset:49152
	ds_read_b128 v[190:193], v155 offset:50176
	ds_read_b128 v[194:197], v155 offset:51200
	ds_read_b128 v[202:205], v155 offset:52224
	ds_read_b128 v[206:209], v155 offset:53248
	ds_read_b128 v[210:213], v155 offset:54272
	ds_read_b128 v[214:217], v155 offset:55296
	ds_read_b128 v[218:221], v155 offset:56320
	global_load_lds_dwordx4 v132, s[70:71]
	s_add_i32 m0, s28, 0x2000
	s_add_u32 s26, s26, 0x80080
	s_addc_u32 s27, s27, 0
	s_add_i32 s28, s67, s38
	global_load_lds_dwordx4 v136, s[70:71]
	s_mov_b32 m0, s28
	s_nop 0
	global_load_lds_dwordx4 v132, s[26:27]
	s_add_i32 m0, s28, 0x2000
	s_nop 0
	global_load_lds_dwordx4 v136, s[26:27]
	s_mov_b32 m0, s45
	s_nop 0
	global_load_lds_dwordx4 v130, s[74:75]
	s_mov_b32 m0, s52
	s_nop 0
	global_load_lds_dwordx4 v134, s[74:75]
	s_waitcnt vmcnt(8)
	s_waitcnt lgkmcnt(0)
	s_barrier
	s_waitcnt lgkmcnt(0)
	v_mfma_f32_16x16x32_bf16 v[62:65], v[146:149], v[186:189], v[62:65]
	v_mfma_f32_16x16x32_bf16 v[58:61], v[162:165], v[186:189], v[58:61]
	v_mfma_f32_16x16x32_bf16 v[46:49], v[146:149], v[194:197], v[46:49]
	v_mfma_f32_16x16x32_bf16 v[42:45], v[162:165], v[194:197], v[42:45]
	v_mfma_f32_16x16x32_bf16 v[30:33], v[146:149], v[206:209], v[30:33]
	v_mfma_f32_16x16x32_bf16 v[26:29], v[162:165], v[206:209], v[26:29]
	v_mfma_f32_16x16x32_bf16 v[14:17], v[146:149], v[214:217], v[14:17]
	v_mfma_f32_16x16x32_bf16 v[10:13], v[162:165], v[214:217], v[10:13]
	v_mfma_f32_16x16x32_bf16 v[62:65], v[158:161], v[190:193], v[62:65]
	v_mfma_f32_16x16x32_bf16 v[58:61], v[166:169], v[190:193], v[58:61]
	v_mfma_f32_16x16x32_bf16 v[46:49], v[158:161], v[202:205], v[46:49]
	v_mfma_f32_16x16x32_bf16 v[42:45], v[166:169], v[202:205], v[42:45]
	v_mfma_f32_16x16x32_bf16 v[30:33], v[158:161], v[210:213], v[30:33]
	v_mfma_f32_16x16x32_bf16 v[26:29], v[166:169], v[210:213], v[26:29]
	v_mfma_f32_16x16x32_bf16 v[14:17], v[158:161], v[218:221], v[14:17]
	v_mfma_f32_16x16x32_bf16 v[10:13], v[166:169], v[218:221], v[10:13]
	v_mfma_f32_16x16x32_bf16 v[54:57], v[170:173], v[186:189], v[54:57]
	v_mfma_f32_16x16x32_bf16 v[50:53], v[178:181], v[186:189], v[50:53]
	v_mfma_f32_16x16x32_bf16 v[38:41], v[170:173], v[194:197], v[38:41]
	v_mfma_f32_16x16x32_bf16 v[34:37], v[178:181], v[194:197], v[34:37]
	v_mfma_f32_16x16x32_bf16 v[22:25], v[170:173], v[206:209], v[22:25]
	v_mfma_f32_16x16x32_bf16 v[18:21], v[178:181], v[206:209], v[18:21]
	v_mfma_f32_16x16x32_bf16 v[6:9], v[170:173], v[214:217], v[6:9]
	v_mfma_f32_16x16x32_bf16 v[2:5], v[178:181], v[214:217], v[2:5]
	v_mfma_f32_16x16x32_bf16 v[54:57], v[174:177], v[190:193], v[54:57]
	v_mfma_f32_16x16x32_bf16 v[50:53], v[182:185], v[190:193], v[50:53]
	v_mfma_f32_16x16x32_bf16 v[38:41], v[174:177], v[202:205], v[38:41]
	v_mfma_f32_16x16x32_bf16 v[34:37], v[182:185], v[202:205], v[34:37]
	v_mfma_f32_16x16x32_bf16 v[22:25], v[174:177], v[210:213], v[22:25]
	v_mfma_f32_16x16x32_bf16 v[18:21], v[182:185], v[210:213], v[18:21]
	v_mfma_f32_16x16x32_bf16 v[6:9], v[174:177], v[218:221], v[6:9]
	v_mfma_f32_16x16x32_bf16 v[2:5], v[182:185], v[218:221], v[2:5]
	s_barrier
	s_add_i32 s65, s65, 2
	s_add_u32 s24, s24, 0x100
	s_addc_u32 s25, s25, 0
	s_add_u32 s59, s59, 0x100
	s_addc_u32 s64, s64, 0
	s_cmp_gt_u32 s65, 29
	s_cbranch_scc0 .LBB0_1177
	s_and_b64 vcc, exec, s[14:15]
	s_cbranch_vccz .LBB0_1180
	s_barrier
